# v47 + GEMM (in-proj, kv_b, FFN1): peeled first k-iteration per tile with vmcnt waits relaxed by the 16 in-flight epilogue stores
# speedup vs baseline: 1.0018x; 1.0018x over previous
.LBB0_265:
	s_lshl_b32 s4, s4, 5
	s_and_b32 s9, s4, 0x60
	s_mov_b64 s[4:5], 0x80
	s_add_i32 m0, s21, 0x18000
	v_lshl_add_u64 v[8:9], v[8:9], 0, s[4:5]
	s_lshl_b32 s8, s3, 13
	s_lshl_b32 s16, s9, 7
	s_waitcnt vmcnt(2)
	s_barrier
	global_load_lds_dwordx4 v[8:9], off
	v_lshl_add_u64 v[6:7], v[6:7], 0, s[4:5]
	s_add_i32 m0, s21, 0x1a000
	s_add_i32 s41, s21, 0x8000
	s_add_i32 s42, s21, 0xa000
	global_load_lds_dwordx4 v[6:7], off
	v_lshl_add_u64 v[4:5], v[4:5], 0, s[4:5]
	s_mov_b32 m0, s41
	s_add_u32 s6, s24, 0x80080
	global_load_lds_dwordx4 v[4:5], off
	v_lshl_add_u64 v[2:3], v[2:3], 0, s[4:5]
	s_mov_b32 m0, s42
	s_addc_u32 s7, s25, 0
	global_load_lds_dwordx4 v[2:3], off
	s_add_i32 m0, s21, 0x1c000
	v_lshl_add_u64 v[2:3], s[6:7], 0, v[134:135]
	global_load_lds_dwordx4 v[2:3], off
	v_lshl_add_u64 v[2:3], s[6:7], 0, v[130:131]
	s_add_i32 m0, s21, 0x1e000
	s_add_i32 s45, 0, 0x10000
	global_load_lds_dwordx4 v[2:3], off
	v_lshrrev_b32_e32 v3, 1, v11
	v_and_b32_e32 v3, 24, v3
	v_and_b32_e32 v2, 15, v11
	v_lshlrev_b32_e32 v4, 1, v3
	v_lshl_or_b32 v1, s3, 6, v2
	v_lshl_or_b32 v2, v2, 6, v4
	v_lshlrev_b32_e32 v4, 2, v11
	v_and_b32_e32 v4, 32, v4
	v_bitop3_b32 v5, v2, s8, v4 bitop3:0xde
	v_bitop3_b32 v150, v2, s16, v4 bitop3:0xde
	v_lshlrev_b32_e32 v2, 15, v15
	v_and_b32_e32 v2, 0xffff0000, v2
	v_or_b32_e32 v151, s9, v3
	v_lshl_add_u32 v2, v14, 12, v2
	v_and_b32_e32 v3, 1, v15
	v_lshl_or_b32 v2, v3, 6, v2
	v_lshl_add_u32 v138, v16, 1, v2
	v_lshlrev_b32_e32 v2, 15, v10
	v_and_b32_e32 v2, 0xffff0000, v2
	s_waitcnt vmcnt(6)
	v_lshl_add_u32 v2, v12, 12, v2
	v_and_b32_e32 v3, 1, v10
	v_lshl_or_b32 v2, v3, 6, v2
	s_add_i32 s46, 0, 0x14000
	s_sext_i32_i8 s52, s2
	s_ashr_i32 s43, s72, 31
	s_mov_b32 s44, s72
	v_mov_b32_e32 v139, v135
	v_lshl_add_u32 v140, v13, 1, v2
	v_mov_b32_e32 v141, v135
	v_mov_b64_e32 v[142:143], 0x780
	v_mov_b64_e32 v[144:145], 0x77f
	v_add_u32_e32 v152, s45, v150
	v_add_u32_e32 v153, 0, v5
	v_add_u32_e32 v154, s46, v150
	s_movk_i32 s47, 0x1e00
	s_barrier
	s_mov_b32 s98, 0

.LBB0_268:
	s_ashr_i32 s9, s8, 31
	v_cmp_lt_i64_e32 vcc, s[16:17], v[142:143]
	s_lshl_b64 s[16:17], s[8:9], 20
	s_add_u32 s16, s88, s16
	s_addc_u32 s17, s89, s17
	s_and_b64 s[18:19], vcc, exec
	s_cselect_b32 s9, s17, s23
	s_cselect_b32 s53, s16, s22
	s_ashr_i32 s7, s6, 31
	s_lshl_b64 s[18:19], s[6:7], 20
	s_add_u32 s18, s38, s18
	s_addc_u32 s19, s39, s19
	s_and_b64 s[26:27], vcc, exec
	s_cselect_b32 s7, s19, s25
	s_cselect_b32 s58, s18, s24
	s_add_u32 s22, s22, 0x80080
	s_addc_u32 s23, s23, 0
	s_add_u32 s59, s24, 0x100
	v_mov_b32_e32 v2, 0
	s_addc_u32 s60, s25, 0
	s_mov_b32 s61, -2
	v_mov_b32_e32 v3, v2
	v_mov_b32_e32 v4, v2
	v_mov_b32_e32 v5, v2
	v_mov_b32_e32 v6, v2
	v_mov_b32_e32 v7, v2
	v_mov_b32_e32 v8, v2
	v_mov_b32_e32 v9, v2
	v_mov_b32_e32 v10, v2
	v_mov_b32_e32 v11, v2
	v_mov_b32_e32 v12, v2
	v_mov_b32_e32 v13, v2
	v_mov_b32_e32 v18, v2
	v_mov_b32_e32 v19, v2
	v_mov_b32_e32 v20, v2
	v_mov_b32_e32 v21, v2
	v_mov_b32_e32 v26, v2
	v_mov_b32_e32 v27, v2
	v_mov_b32_e32 v28, v2
	v_mov_b32_e32 v29, v2
	v_mov_b32_e32 v34, v2
	v_mov_b32_e32 v35, v2
	v_mov_b32_e32 v36, v2
	v_mov_b32_e32 v37, v2
	v_mov_b32_e32 v42, v2
	v_mov_b32_e32 v43, v2
	v_mov_b32_e32 v44, v2
	v_mov_b32_e32 v45, v2
	v_mov_b32_e32 v50, v2
	v_mov_b32_e32 v51, v2
	v_mov_b32_e32 v52, v2
	v_mov_b32_e32 v53, v2
	v_mov_b32_e32 v14, v2
	v_mov_b32_e32 v15, v2
	v_mov_b32_e32 v16, v2
	v_mov_b32_e32 v17, v2
	v_mov_b32_e32 v22, v2
	v_mov_b32_e32 v23, v2
	v_mov_b32_e32 v24, v2
	v_mov_b32_e32 v25, v2
	v_mov_b32_e32 v30, v2
	v_mov_b32_e32 v31, v2
	v_mov_b32_e32 v32, v2
	v_mov_b32_e32 v33, v2
	v_mov_b32_e32 v38, v2
	v_mov_b32_e32 v39, v2
	v_mov_b32_e32 v40, v2
	v_mov_b32_e32 v41, v2
	v_mov_b32_e32 v46, v2
	v_mov_b32_e32 v47, v2
	v_mov_b32_e32 v48, v2
	v_mov_b32_e32 v49, v2
	v_mov_b32_e32 v54, v2
	v_mov_b32_e32 v55, v2
	v_mov_b32_e32 v56, v2
	v_mov_b32_e32 v57, v2
	v_mov_b32_e32 v58, v2
	v_mov_b32_e32 v59, v2
	v_mov_b32_e32 v60, v2
	v_mov_b32_e32 v61, v2
	v_mov_b32_e32 v62, v2
	v_mov_b32_e32 v63, v2
	v_mov_b32_e32 v64, v2
	v_mov_b32_e32 v65, v2
	v_mov_b32_e32 v66, v2
	v_mov_b32_e32 v67, v2
	v_mov_b32_e32 v68, v2
	v_mov_b32_e32 v69, v2
	v_mov_b32_e32 v70, v2
	v_mov_b32_e32 v71, v2
	v_mov_b32_e32 v72, v2
	v_mov_b32_e32 v73, v2
	v_mov_b32_e32 v74, v2
	v_mov_b32_e32 v75, v2
	v_mov_b32_e32 v76, v2
	v_mov_b32_e32 v77, v2
	v_mov_b32_e32 v82, v2
	v_mov_b32_e32 v83, v2
	v_mov_b32_e32 v84, v2
	v_mov_b32_e32 v85, v2
	v_mov_b32_e32 v90, v2
	v_mov_b32_e32 v91, v2
	v_mov_b32_e32 v92, v2
	v_mov_b32_e32 v93, v2
	v_mov_b32_e32 v98, v2
	v_mov_b32_e32 v99, v2
	v_mov_b32_e32 v100, v2
	v_mov_b32_e32 v101, v2
	v_mov_b32_e32 v106, v2
	v_mov_b32_e32 v107, v2
	v_mov_b32_e32 v108, v2
	v_mov_b32_e32 v109, v2
	v_mov_b32_e32 v114, v2
	v_mov_b32_e32 v115, v2
	v_mov_b32_e32 v116, v2
	v_mov_b32_e32 v117, v2
	v_mov_b32_e32 v78, v2
	v_mov_b32_e32 v79, v2
	v_mov_b32_e32 v80, v2
	v_mov_b32_e32 v81, v2
	v_mov_b32_e32 v86, v2
	v_mov_b32_e32 v87, v2
	v_mov_b32_e32 v88, v2
	v_mov_b32_e32 v89, v2
	v_mov_b32_e32 v94, v2
	v_mov_b32_e32 v95, v2
	v_mov_b32_e32 v96, v2
	v_mov_b32_e32 v97, v2
	v_mov_b32_e32 v102, v2
	v_mov_b32_e32 v103, v2
	v_mov_b32_e32 v104, v2
	v_mov_b32_e32 v105, v2
	v_mov_b32_e32 v110, v2
	v_mov_b32_e32 v111, v2
	v_mov_b32_e32 v112, v2
	v_mov_b32_e32 v113, v2
	v_mov_b32_e32 v118, v2
	v_mov_b32_e32 v119, v2
	v_mov_b32_e32 v120, v2
	v_mov_b32_e32 v121, v2
	v_mov_b32_e32 v122, v2
	v_mov_b32_e32 v123, v2
	v_mov_b32_e32 v124, v2
	v_mov_b32_e32 v125, v2
	v_mov_b32_e32 v126, v2
	v_mov_b32_e32 v127, v2
	v_mov_b32_e32 v128, v2
	v_mov_b32_e32 v129, v2
	s_cmp_eq_u32 s98, 0
	s_cbranch_scc1 .LBB0_269
	ds_read_b128 v[146:149], v152
	ds_read_b128 v[156:159], v152 offset:1024
	ds_read_b128 v[160:163], v152 offset:2048
	ds_read_b128 v[164:167], v152 offset:3072
	s_add_u32 s24, s22, 0xfff80080
	s_addc_u32 s25, s23, -1
	s_cmp_eq_u32 s61, 28
	s_cselect_b32 s27, s9, s25
	s_cselect_b32 s26, s53, s24
	s_cselect_b32 s25, s7, s60
	s_cselect_b32 s24, s58, s59
	v_lshl_add_u64 v[202:203], s[22:23], 0, v[138:139]
	s_add_i32 m0, s21, 0xc000
	ds_read_b128 v[168:171], v153
	ds_read_b128 v[172:175], v153 offset:1024
	ds_read_b128 v[176:179], v153 offset:2048
	ds_read_b128 v[180:183], v153 offset:3072
	ds_read_b128 v[186:189], v153 offset:4096
	ds_read_b128 v[190:193], v153 offset:5120
	ds_read_b128 v[194:197], v153 offset:6144
	ds_read_b128 v[198:201], v153 offset:7168
	global_load_lds_dwordx4 v[202:203], off
	v_lshl_add_u64 v[202:203], s[22:23], 0, v[140:141]
	s_add_i32 m0, s21, 0xe000
	s_nop 0
	global_load_lds_dwordx4 v[202:203], off
	ds_read_b128 v[202:205], v154
	ds_read_b128 v[206:209], v154 offset:1024
	ds_read_b128 v[210:213], v154 offset:2048
	ds_read_b128 v[214:217], v154 offset:3072
	s_waitcnt vmcnt(24)
	s_waitcnt lgkmcnt(0)
	s_barrier
	s_setprio 1
	v_mfma_f32_16x16x32_bf16 v[126:129], v[146:149], v[168:171], v[126:129]
	v_mfma_f32_16x16x32_bf16 v[122:125], v[160:163], v[168:171], v[122:125]
	v_mfma_f32_16x16x32_bf16 v[118:121], v[146:149], v[176:179], v[118:121]
	v_mfma_f32_16x16x32_bf16 v[110:113], v[160:163], v[176:179], v[110:113]
	v_mfma_f32_16x16x32_bf16 v[102:105], v[146:149], v[186:189], v[102:105]
	v_mfma_f32_16x16x32_bf16 v[94:97], v[160:163], v[186:189], v[94:97]
	v_mfma_f32_16x16x32_bf16 v[86:89], v[146:149], v[194:197], v[86:89]
	v_mfma_f32_16x16x32_bf16 v[78:81], v[160:163], v[194:197], v[78:81]
	v_mfma_f32_16x16x32_bf16 v[126:129], v[156:159], v[172:175], v[126:129]
	v_mfma_f32_16x16x32_bf16 v[122:125], v[164:167], v[172:175], v[122:125]
	v_mfma_f32_16x16x32_bf16 v[118:121], v[156:159], v[180:183], v[118:121]
	v_mfma_f32_16x16x32_bf16 v[110:113], v[164:167], v[180:183], v[110:113]
	v_mfma_f32_16x16x32_bf16 v[102:105], v[156:159], v[190:193], v[102:105]
	v_mfma_f32_16x16x32_bf16 v[94:97], v[164:167], v[190:193], v[94:97]
	v_mfma_f32_16x16x32_bf16 v[86:89], v[156:159], v[198:201], v[86:89]
	v_mfma_f32_16x16x32_bf16 v[78:81], v[164:167], v[198:201], v[78:81]
	v_mfma_f32_16x16x32_bf16 v[114:117], v[202:205], v[168:171], v[114:117]
	v_mfma_f32_16x16x32_bf16 v[106:109], v[210:213], v[168:171], v[106:109]
	v_mfma_f32_16x16x32_bf16 v[98:101], v[202:205], v[176:179], v[98:101]
	v_mfma_f32_16x16x32_bf16 v[90:93], v[210:213], v[176:179], v[90:93]
	v_mfma_f32_16x16x32_bf16 v[82:85], v[202:205], v[186:189], v[82:85]
	v_mfma_f32_16x16x32_bf16 v[74:77], v[210:213], v[186:189], v[74:77]
	v_mfma_f32_16x16x32_bf16 v[70:73], v[202:205], v[194:197], v[70:73]
	v_mfma_f32_16x16x32_bf16 v[66:69], v[210:213], v[194:197], v[66:69]
	v_mfma_f32_16x16x32_bf16 v[114:117], v[206:209], v[172:175], v[114:117]
	v_mfma_f32_16x16x32_bf16 v[106:109], v[214:217], v[172:175], v[106:109]
	v_mfma_f32_16x16x32_bf16 v[98:101], v[206:209], v[180:183], v[98:101]
	v_mfma_f32_16x16x32_bf16 v[90:93], v[214:217], v[180:183], v[90:93]
	v_mfma_f32_16x16x32_bf16 v[82:85], v[206:209], v[190:193], v[82:85]
	v_mfma_f32_16x16x32_bf16 v[74:77], v[214:217], v[190:193], v[74:77]
	v_mfma_f32_16x16x32_bf16 v[70:73], v[206:209], v[198:201], v[70:73]
	v_mfma_f32_16x16x32_bf16 v[66:69], v[214:217], v[198:201], v[66:69]
	s_setprio 0
	s_barrier
	s_add_i32 s68, s45, s29
	v_lshl_add_u64 v[218:219], s[24:25], 0, v[134:135]
	s_mov_b32 m0, s68
	global_load_lds_dwordx4 v[218:219], off
	v_lshl_add_u64 v[220:221], s[24:25], 0, v[130:131]
	s_add_i32 m0, s68, 0x2000
	s_nop 0
	global_load_lds_dwordx4 v[220:221], off
	s_mov_b32 m0, s21
	v_lshl_add_u64 v[222:223], s[26:27], 0, v[136:137]
	ds_read_b128 v[168:171], v153 offset:16384
	ds_read_b128 v[172:175], v153 offset:17408
	ds_read_b128 v[176:179], v153 offset:18432
	ds_read_b128 v[180:183], v153 offset:19456
	ds_read_b128 v[186:189], v153 offset:20480
	ds_read_b128 v[190:193], v153 offset:21504
	ds_read_b128 v[194:197], v153 offset:22528
	ds_read_b128 v[198:201], v153 offset:23552
	global_load_lds_dwordx4 v[222:223], off
	v_lshl_add_u64 v[224:225], s[26:27], 0, v[132:133]
	s_mov_b32 m0, s34
	s_nop 0
	global_load_lds_dwordx4 v[224:225], off
	s_waitcnt vmcnt(22)
	s_waitcnt lgkmcnt(0)
	s_barrier
	s_setprio 1
	v_mfma_f32_16x16x32_bf16 v[62:65], v[146:149], v[168:171], v[62:65]
	v_mfma_f32_16x16x32_bf16 v[58:61], v[160:163], v[168:171], v[58:61]
	v_mfma_f32_16x16x32_bf16 v[54:57], v[146:149], v[176:179], v[54:57]
	v_mfma_f32_16x16x32_bf16 v[46:49], v[160:163], v[176:179], v[46:49]
	v_mfma_f32_16x16x32_bf16 v[38:41], v[146:149], v[186:189], v[38:41]
	v_mfma_f32_16x16x32_bf16 v[30:33], v[160:163], v[186:189], v[30:33]
	v_mfma_f32_16x16x32_bf16 v[22:25], v[146:149], v[194:197], v[22:25]
	v_mfma_f32_16x16x32_bf16 v[14:17], v[160:163], v[194:197], v[14:17]
	v_mfma_f32_16x16x32_bf16 v[62:65], v[156:159], v[172:175], v[62:65]
	v_mfma_f32_16x16x32_bf16 v[58:61], v[164:167], v[172:175], v[58:61]
	v_mfma_f32_16x16x32_bf16 v[54:57], v[156:159], v[180:183], v[54:57]
	v_mfma_f32_16x16x32_bf16 v[46:49], v[164:167], v[180:183], v[46:49]
	v_mfma_f32_16x16x32_bf16 v[38:41], v[156:159], v[190:193], v[38:41]
	v_mfma_f32_16x16x32_bf16 v[30:33], v[164:167], v[190:193], v[30:33]
	v_mfma_f32_16x16x32_bf16 v[22:25], v[156:159], v[198:201], v[22:25]
	v_mfma_f32_16x16x32_bf16 v[14:17], v[164:167], v[198:201], v[14:17]
	v_mfma_f32_16x16x32_bf16 v[50:53], v[202:205], v[168:171], v[50:53]
	v_mfma_f32_16x16x32_bf16 v[42:45], v[210:213], v[168:171], v[42:45]
	v_mfma_f32_16x16x32_bf16 v[34:37], v[202:205], v[176:179], v[34:37]
	v_mfma_f32_16x16x32_bf16 v[26:29], v[210:213], v[176:179], v[26:29]
	v_mfma_f32_16x16x32_bf16 v[18:21], v[202:205], v[186:189], v[18:21]
	v_mfma_f32_16x16x32_bf16 v[10:13], v[210:213], v[186:189], v[10:13]
	v_mfma_f32_16x16x32_bf16 v[6:9], v[202:205], v[194:197], v[6:9]
	v_mfma_f32_16x16x32_bf16 v[2:5], v[210:213], v[194:197], v[2:5]
	v_mfma_f32_16x16x32_bf16 v[50:53], v[206:209], v[172:175], v[50:53]
	v_mfma_f32_16x16x32_bf16 v[42:45], v[214:217], v[172:175], v[42:45]
	v_mfma_f32_16x16x32_bf16 v[34:37], v[206:209], v[180:183], v[34:37]
	v_mfma_f32_16x16x32_bf16 v[26:29], v[214:217], v[180:183], v[26:29]
	v_mfma_f32_16x16x32_bf16 v[18:21], v[206:209], v[190:193], v[18:21]
	v_mfma_f32_16x16x32_bf16 v[10:13], v[214:217], v[190:193], v[10:13]
	v_mfma_f32_16x16x32_bf16 v[6:9], v[206:209], v[198:201], v[6:9]
	v_mfma_f32_16x16x32_bf16 v[2:5], v[214:217], v[198:201], v[2:5]
	s_setprio 0
	s_barrier
	s_add_u32 s68, s24, 0x80000
	s_addc_u32 s69, s25, 0
	s_add_i32 s70, s46, s29
	v_lshl_add_u64 v[146:147], s[68:69], 0, v[134:135]
	s_mov_b32 m0, s70
	s_nop 0
	global_load_lds_dwordx4 v[146:147], off
	v_lshl_add_u64 v[146:147], s[68:69], 0, v[130:131]
	s_add_i32 m0, s70, 0x2000
	s_nop 0
	global_load_lds_dwordx4 v[146:147], off
	s_add_i32 s68, 0, 0x18000
	v_add_u32_e32 v155, s68, v150
	ds_read_b128 v[146:149], v155
	ds_read_b128 v[156:159], v155 offset:1024
	ds_read_b128 v[160:163], v155 offset:2048
	ds_read_b128 v[164:167], v155 offset:3072
	s_add_u32 s26, s26, 0x80000
	s_addc_u32 s27, s27, 0
	s_mov_b32 m0, s35
	v_lshl_add_u64 v[202:203], s[26:27], 0, v[136:137]
	ds_read_b128 v[168:171], v153 offset:32768
	ds_read_b128 v[172:175], v153 offset:33792
	ds_read_b128 v[176:179], v153 offset:34816
	ds_read_b128 v[180:183], v153 offset:35840
	ds_read_b128 v[186:189], v153 offset:36864
	ds_read_b128 v[190:193], v153 offset:37888
	ds_read_b128 v[194:197], v153 offset:38912
	ds_read_b128 v[198:201], v153 offset:39936
	global_load_lds_dwordx4 v[202:203], off
	v_lshl_add_u64 v[202:203], s[26:27], 0, v[132:133]
	s_mov_b32 m0, s36
	s_nop 0
	global_load_lds_dwordx4 v[202:203], off
	v_add_u32_e32 v214, 0x1c000, v150
	ds_read_b128 v[202:205], v214
	ds_read_b128 v[206:209], v214 offset:1024
	ds_read_b128 v[210:213], v214 offset:2048
	ds_read_b128 v[214:217], v214 offset:3072
	s_waitcnt vmcnt(8)
	s_waitcnt lgkmcnt(0)
	s_barrier
	s_setprio 1
	v_mfma_f32_16x16x32_bf16 v[126:129], v[146:149], v[168:171], v[126:129]
	v_mfma_f32_16x16x32_bf16 v[122:125], v[160:163], v[168:171], v[122:125]
	v_mfma_f32_16x16x32_bf16 v[118:121], v[146:149], v[176:179], v[118:121]
	v_mfma_f32_16x16x32_bf16 v[110:113], v[160:163], v[176:179], v[110:113]
	v_mfma_f32_16x16x32_bf16 v[102:105], v[146:149], v[186:189], v[102:105]
	v_mfma_f32_16x16x32_bf16 v[94:97], v[160:163], v[186:189], v[94:97]
	v_mfma_f32_16x16x32_bf16 v[86:89], v[146:149], v[194:197], v[86:89]
	v_mfma_f32_16x16x32_bf16 v[78:81], v[160:163], v[194:197], v[78:81]
	v_mfma_f32_16x16x32_bf16 v[126:129], v[156:159], v[172:175], v[126:129]
	v_mfma_f32_16x16x32_bf16 v[122:125], v[164:167], v[172:175], v[122:125]
	v_mfma_f32_16x16x32_bf16 v[118:121], v[156:159], v[180:183], v[118:121]
	v_mfma_f32_16x16x32_bf16 v[110:113], v[164:167], v[180:183], v[110:113]
	v_mfma_f32_16x16x32_bf16 v[102:105], v[156:159], v[190:193], v[102:105]
	v_mfma_f32_16x16x32_bf16 v[94:97], v[164:167], v[190:193], v[94:97]
	v_mfma_f32_16x16x32_bf16 v[86:89], v[156:159], v[198:201], v[86:89]
	v_mfma_f32_16x16x32_bf16 v[78:81], v[164:167], v[198:201], v[78:81]
	v_mfma_f32_16x16x32_bf16 v[114:117], v[202:205], v[168:171], v[114:117]
	v_mfma_f32_16x16x32_bf16 v[106:109], v[210:213], v[168:171], v[106:109]
	v_mfma_f32_16x16x32_bf16 v[98:101], v[202:205], v[176:179], v[98:101]
	v_mfma_f32_16x16x32_bf16 v[90:93], v[210:213], v[176:179], v[90:93]
	v_mfma_f32_16x16x32_bf16 v[82:85], v[202:205], v[186:189], v[82:85]
	v_mfma_f32_16x16x32_bf16 v[74:77], v[210:213], v[186:189], v[74:77]
	v_mfma_f32_16x16x32_bf16 v[70:73], v[202:205], v[194:197], v[70:73]
	v_mfma_f32_16x16x32_bf16 v[66:69], v[210:213], v[194:197], v[66:69]
	v_mfma_f32_16x16x32_bf16 v[114:117], v[206:209], v[172:175], v[114:117]
	v_mfma_f32_16x16x32_bf16 v[106:109], v[214:217], v[172:175], v[106:109]
	v_mfma_f32_16x16x32_bf16 v[98:101], v[206:209], v[180:183], v[98:101]
	v_mfma_f32_16x16x32_bf16 v[90:93], v[214:217], v[180:183], v[90:93]
	v_mfma_f32_16x16x32_bf16 v[82:85], v[206:209], v[190:193], v[82:85]
	v_mfma_f32_16x16x32_bf16 v[74:77], v[214:217], v[190:193], v[74:77]
	v_mfma_f32_16x16x32_bf16 v[70:73], v[206:209], v[198:201], v[70:73]
	v_mfma_f32_16x16x32_bf16 v[66:69], v[214:217], v[198:201], v[66:69]
	s_setprio 0
	s_barrier
	s_add_i32 s26, 0, 0x1c000
	s_add_i32 s27, s68, s29
	v_lshl_add_u64 v[218:219], v[218:219], 0, s[4:5]
	s_mov_b32 m0, s27
	global_load_lds_dwordx4 v[218:219], off
	v_lshl_add_u64 v[218:219], v[220:221], 0, s[4:5]
	s_add_i32 m0, s27, 0x2000
	s_nop 0
	global_load_lds_dwordx4 v[218:219], off
	s_mov_b32 m0, s41
	v_lshl_add_u64 v[218:219], v[222:223], 0, s[4:5]
	ds_read_b128 v[168:171], v153 offset:49152
	ds_read_b128 v[172:175], v153 offset:50176
	ds_read_b128 v[176:179], v153 offset:51200
	ds_read_b128 v[180:183], v153 offset:52224
	ds_read_b128 v[186:189], v153 offset:53248
	ds_read_b128 v[190:193], v153 offset:54272
	ds_read_b128 v[194:197], v153 offset:55296
	ds_read_b128 v[198:201], v153 offset:56320
	global_load_lds_dwordx4 v[218:219], off
	v_lshl_add_u64 v[218:219], v[224:225], 0, s[4:5]
	s_mov_b32 m0, s42
	s_nop 0
	global_load_lds_dwordx4 v[218:219], off
	s_add_u32 s24, s24, 0x80080
	s_addc_u32 s25, s25, 0
	s_add_i32 s26, s26, s29
	v_lshl_add_u64 v[218:219], s[24:25], 0, v[134:135]
	s_mov_b32 m0, s26
	s_nop 0
	global_load_lds_dwordx4 v[218:219], off
	v_lshl_add_u64 v[218:219], s[24:25], 0, v[130:131]
	s_add_i32 m0, s26, 0x2000
	s_nop 0
	global_load_lds_dwordx4 v[218:219], off
	s_waitcnt vmcnt(8)
	s_waitcnt lgkmcnt(0)
	s_barrier
	s_setprio 1
	v_mfma_f32_16x16x32_bf16 v[62:65], v[146:149], v[168:171], v[62:65]
	v_mfma_f32_16x16x32_bf16 v[58:61], v[160:163], v[168:171], v[58:61]
	v_mfma_f32_16x16x32_bf16 v[54:57], v[146:149], v[176:179], v[54:57]
	v_mfma_f32_16x16x32_bf16 v[46:49], v[160:163], v[176:179], v[46:49]
	v_mfma_f32_16x16x32_bf16 v[38:41], v[146:149], v[186:189], v[38:41]
	v_mfma_f32_16x16x32_bf16 v[30:33], v[160:163], v[186:189], v[30:33]
	v_mfma_f32_16x16x32_bf16 v[22:25], v[146:149], v[194:197], v[22:25]
	v_mfma_f32_16x16x32_bf16 v[14:17], v[160:163], v[194:197], v[14:17]
	v_mfma_f32_16x16x32_bf16 v[62:65], v[156:159], v[172:175], v[62:65]
	v_mfma_f32_16x16x32_bf16 v[58:61], v[164:167], v[172:175], v[58:61]
	v_mfma_f32_16x16x32_bf16 v[54:57], v[156:159], v[180:183], v[54:57]
	v_mfma_f32_16x16x32_bf16 v[46:49], v[164:167], v[180:183], v[46:49]
	v_mfma_f32_16x16x32_bf16 v[38:41], v[156:159], v[190:193], v[38:41]
	v_mfma_f32_16x16x32_bf16 v[30:33], v[164:167], v[190:193], v[30:33]
	v_mfma_f32_16x16x32_bf16 v[22:25], v[156:159], v[198:201], v[22:25]
	v_mfma_f32_16x16x32_bf16 v[14:17], v[164:167], v[198:201], v[14:17]
	v_mfma_f32_16x16x32_bf16 v[50:53], v[202:205], v[168:171], v[50:53]
	v_mfma_f32_16x16x32_bf16 v[42:45], v[210:213], v[168:171], v[42:45]
	v_mfma_f32_16x16x32_bf16 v[34:37], v[202:205], v[176:179], v[34:37]
	v_mfma_f32_16x16x32_bf16 v[26:29], v[210:213], v[176:179], v[26:29]
	v_mfma_f32_16x16x32_bf16 v[18:21], v[202:205], v[186:189], v[18:21]
	v_mfma_f32_16x16x32_bf16 v[10:13], v[210:213], v[186:189], v[10:13]
	v_mfma_f32_16x16x32_bf16 v[6:9], v[202:205], v[194:197], v[6:9]
	v_mfma_f32_16x16x32_bf16 v[2:5], v[210:213], v[194:197], v[2:5]
	v_mfma_f32_16x16x32_bf16 v[50:53], v[206:209], v[172:175], v[50:53]
	v_mfma_f32_16x16x32_bf16 v[42:45], v[214:217], v[172:175], v[42:45]
	v_mfma_f32_16x16x32_bf16 v[34:37], v[206:209], v[180:183], v[34:37]
	v_mfma_f32_16x16x32_bf16 v[26:29], v[214:217], v[180:183], v[26:29]
	v_mfma_f32_16x16x32_bf16 v[18:21], v[206:209], v[190:193], v[18:21]
	v_mfma_f32_16x16x32_bf16 v[10:13], v[214:217], v[190:193], v[10:13]
	v_mfma_f32_16x16x32_bf16 v[6:9], v[206:209], v[198:201], v[6:9]
	v_mfma_f32_16x16x32_bf16 v[2:5], v[214:217], v[198:201], v[2:5]
	s_setprio 0
	s_add_i32 s61, s61, 2
	s_add_u32 s22, s22, 0x100
	s_addc_u32 s23, s23, 0
	s_add_u32 s59, s59, 0x100
	s_addc_u32 s60, s60, 0
	s_cmp_gt_u32 s61, 29
	s_barrier
	s_cbranch_scc1 .Lgemm_epi_0

.Lgemm_epi_0:
	v_lshl_or_b32 v148, s52, 8, v151
	v_lshl_add_u32 v155, s20, 8, v1
	v_ashrrev_i32_e32 v149, 31, v148
	v_mov_b64_e32 v[146:147], s[54:55]
	v_mad_i64_i32 v[156:157], s[22:23], v155, s47, v[146:147]
	v_lshlrev_b64 v[148:149], 1, v[148:149]
	v_lshl_add_u64 v[156:157], v[156:157], 0, v[148:149]
	v_cvt_pk_bf16_f32 v126, v126, v127
	v_cvt_pk_bf16_f32 v127, v128, v129
	v_cvt_pk_bf16_f32 v128, v122, v123
	v_cvt_pk_bf16_f32 v129, v124, v125
	global_store_dwordx4 v[156:157], v[126:129], off
	v_cvt_pk_bf16_f32 v114, v114, v115
	v_cvt_pk_bf16_f32 v115, v116, v117
	v_cvt_pk_bf16_f32 v116, v106, v107
	v_or_b32_e32 v106, 16, v155
	v_mad_i64_i32 v[106:107], s[22:23], v106, s47, v[146:147]
	v_cvt_pk_bf16_f32 v117, v108, v109
	global_store_dwordx4 v[156:157], v[114:117], off offset:256
	s_and_b64 vcc, exec, s[2:3]
	s_mov_b32 s52, s6
	v_lshl_add_u64 v[114:115], v[106:107], 0, v[148:149]
	v_cvt_pk_bf16_f32 v106, v118, v119
	v_cvt_pk_bf16_f32 v107, v120, v121
	v_cvt_pk_bf16_f32 v108, v110, v111
	v_cvt_pk_bf16_f32 v109, v112, v113
	global_store_dwordx4 v[114:115], v[106:109], off
	v_cvt_pk_bf16_f32 v98, v98, v99
	v_cvt_pk_bf16_f32 v99, v100, v101
	v_cvt_pk_bf16_f32 v100, v90, v91
	v_or_b32_e32 v90, 32, v155
	v_mad_i64_i32 v[90:91], s[22:23], v90, s47, v[146:147]
	v_cvt_pk_bf16_f32 v101, v92, v93
	global_store_dwordx4 v[114:115], v[98:101], off offset:256
	s_mov_b32 s20, s8
	s_mov_b64 s[24:25], s[18:19]
	v_lshl_add_u64 v[98:99], v[90:91], 0, v[148:149]
	v_cvt_pk_bf16_f32 v90, v102, v103
	v_cvt_pk_bf16_f32 v91, v104, v105
	v_cvt_pk_bf16_f32 v92, v94, v95
	v_cvt_pk_bf16_f32 v93, v96, v97
	global_store_dwordx4 v[98:99], v[90:93], off
	v_cvt_pk_bf16_f32 v82, v82, v83
	v_cvt_pk_bf16_f32 v83, v84, v85
	v_cvt_pk_bf16_f32 v84, v74, v75
	v_or_b32_e32 v74, 48, v155
	v_mad_i64_i32 v[74:75], s[22:23], v74, s47, v[146:147]
	v_cvt_pk_bf16_f32 v85, v76, v77
	global_store_dwordx4 v[98:99], v[82:85], off offset:256
	s_nop 1
	v_lshl_add_u64 v[82:83], v[74:75], 0, v[148:149]
	v_cvt_pk_bf16_f32 v74, v86, v87
	v_cvt_pk_bf16_f32 v75, v88, v89
	v_cvt_pk_bf16_f32 v76, v78, v79
	v_cvt_pk_bf16_f32 v77, v80, v81
	global_store_dwordx4 v[82:83], v[74:77], off
	v_cvt_pk_bf16_f32 v70, v70, v71
	v_cvt_pk_bf16_f32 v71, v72, v73
	v_cvt_pk_bf16_f32 v72, v66, v67
	v_add_u32_e32 v66, 0x80, v155
	v_mad_i64_i32 v[66:67], s[22:23], v66, s47, v[146:147]
	v_lshl_add_u64 v[66:67], v[66:67], 0, v[148:149]
	v_cvt_pk_bf16_f32 v73, v68, v69
	global_store_dwordx4 v[82:83], v[70:73], off offset:256
	v_cvt_pk_bf16_f32 v62, v62, v63
	v_cvt_pk_bf16_f32 v63, v64, v65
	v_cvt_pk_bf16_f32 v64, v58, v59
	v_cvt_pk_bf16_f32 v65, v60, v61
	global_store_dwordx4 v[66:67], v[62:65], off
	v_cvt_pk_bf16_f32 v50, v50, v51
	v_cvt_pk_bf16_f32 v51, v52, v53
	v_cvt_pk_bf16_f32 v52, v42, v43
	v_add_u32_e32 v42, 0x90, v155
	v_mad_i64_i32 v[42:43], s[22:23], v42, s47, v[146:147]
	v_cvt_pk_bf16_f32 v53, v44, v45
	global_store_dwordx4 v[66:67], v[50:53], off offset:256
	s_nop 1
	v_lshl_add_u64 v[50:51], v[42:43], 0, v[148:149]
	v_cvt_pk_bf16_f32 v42, v54, v55
	v_cvt_pk_bf16_f32 v43, v56, v57
	v_cvt_pk_bf16_f32 v44, v46, v47
	v_cvt_pk_bf16_f32 v45, v48, v49
	global_store_dwordx4 v[50:51], v[42:45], off
	v_cvt_pk_bf16_f32 v34, v34, v35
	v_cvt_pk_bf16_f32 v35, v36, v37
	v_cvt_pk_bf16_f32 v36, v26, v27
	v_add_u32_e32 v26, 0xa0, v155
	v_mad_i64_i32 v[26:27], s[22:23], v26, s47, v[146:147]
	v_cvt_pk_bf16_f32 v37, v28, v29
	global_store_dwordx4 v[50:51], v[34:37], off offset:256
	s_nop 1
	v_lshl_add_u64 v[34:35], v[26:27], 0, v[148:149]
	v_cvt_pk_bf16_f32 v26, v38, v39
	v_cvt_pk_bf16_f32 v27, v40, v41
	v_cvt_pk_bf16_f32 v28, v30, v31
	v_cvt_pk_bf16_f32 v29, v32, v33
	global_store_dwordx4 v[34:35], v[26:29], off
	v_cvt_pk_bf16_f32 v18, v18, v19
	v_cvt_pk_bf16_f32 v19, v20, v21
	v_cvt_pk_bf16_f32 v20, v10, v11
	v_add_u32_e32 v10, 0xb0, v155
	v_mad_i64_i32 v[10:11], s[22:23], v10, s47, v[146:147]
	v_cvt_pk_bf16_f32 v21, v12, v13
	global_store_dwordx4 v[34:35], v[18:21], off offset:256
	s_mov_b64 s[22:23], s[16:17]
	s_nop 0
	v_lshl_add_u64 v[18:19], v[10:11], 0, v[148:149]
	v_cvt_pk_bf16_f32 v10, v22, v23
	v_cvt_pk_bf16_f32 v11, v24, v25
	v_cvt_pk_bf16_f32 v12, v14, v15
	v_cvt_pk_bf16_f32 v13, v16, v17
	global_store_dwordx4 v[18:19], v[10:13], off
	v_cvt_pk_bf16_f32 v6, v6, v7
	v_cvt_pk_bf16_f32 v7, v8, v9
	v_cvt_pk_bf16_f32 v8, v2, v3
	v_cvt_pk_bf16_f32 v9, v4, v5
	global_store_dwordx4 v[18:19], v[6:9], off offset:256
	s_mov_b32 s98, 1
	s_cbranch_vccz .LBB0_266
	s_waitcnt vmcnt(0)
	s_cmpk_gt_u32 s28, 0xff
	s_cbranch_scc1 .LBB0_273
	s_barrier

.LBB0_447:
	s_lshl_b32 s4, s4, 5
	s_mov_b64 s[6:7], 0x80
	s_and_b32 s4, s4, 0x60
	s_add_i32 m0, s46, 0x18000
	v_lshl_add_u64 v[8:9], v[8:9], 0, s[6:7]
	s_lshl_b32 s16, s5, 13
	s_lshl_b32 s17, s4, 7
	s_waitcnt vmcnt(2)
	s_barrier
	global_load_lds_dwordx4 v[8:9], off
	v_lshl_add_u64 v[6:7], v[6:7], 0, s[6:7]
	s_add_i32 m0, s46, 0x1a000
	s_add_i32 s53, s46, 0x8000
	s_add_i32 s58, s46, 0xa000
	global_load_lds_dwordx4 v[6:7], off
	v_lshl_add_u64 v[4:5], v[4:5], 0, s[6:7]
	s_mov_b32 m0, s53
	s_add_u32 s8, s30, 0x20080
	global_load_lds_dwordx4 v[4:5], off
	v_lshl_add_u64 v[2:3], v[2:3], 0, s[6:7]
	s_mov_b32 m0, s58
	s_addc_u32 s9, s31, 0
	global_load_lds_dwordx4 v[2:3], off
	s_add_i32 m0, s46, 0x1c000
	v_lshl_add_u64 v[2:3], s[8:9], 0, v[132:133]
	global_load_lds_dwordx4 v[2:3], off
	v_lshl_add_u64 v[2:3], s[8:9], 0, v[136:137]
	s_add_i32 m0, s46, 0x1e000
	s_sext_i32_i8 s70, s2
	global_load_lds_dwordx4 v[2:3], off
	v_lshrrev_b32_e32 v3, 1, v10
	v_and_b32_e32 v3, 24, v3
	v_and_b32_e32 v2, 15, v10
	v_lshlrev_b32_e32 v4, 1, v3
	v_lshl_or_b32 v1, s5, 6, v2
	v_lshl_or_b32 v2, v2, 6, v4
	v_lshlrev_b32_e32 v4, 2, v10
	v_and_b32_e32 v4, 32, v4
	v_bitop3_b32 v5, v2, s16, v4 bitop3:0xde
	v_bitop3_b32 v148, v2, s17, v4 bitop3:0xde
	v_or_b32_e32 v149, s4, v3
	v_lshrrev_b32_e32 v3, 1, v11
	v_mul_lo_u32 v2, v13, s3
	s_mov_b32 s2, 0xf000
	v_mad_u64_u32 v[2:3], s[4:5], v3, s2, v[2:3]
	v_or_b32_e32 v2, v2, v12
	v_add_lshl_u32 v2, v2, v14, 1
	v_mov_b32_e32 v3, v133
	s_mov_b64 s[4:5], 0xf0080
	v_lshl_add_u64 v[138:139], v[2:3], 0, s[4:5]
	v_lshrrev_b32_e32 v3, 1, v15
	v_mul_lo_u32 v2, v16, s3
	v_mad_u64_u32 v[2:3], s[2:3], v3, s2, v[2:3]
	s_waitcnt vmcnt(6)
	v_or_b32_e32 v2, v2, v17
	v_add_lshl_u32 v2, v2, v18, 1
	v_mov_b32_e32 v3, v133
	s_add_i32 s61, 0, 0x10000
	s_add_i32 s71, 0, 0x14000
	s_ashr_i32 s59, s72, 31
	s_mov_b32 s60, s72
	v_lshl_add_u64 v[140:141], v[2:3], 0, s[4:5]
	v_mov_b64_e32 v[142:143], 0x400
	v_mov_b64_e32 v[144:145], 0x3ff
	v_add_u32_e32 v150, s61, v148
	v_add_u32_e32 v151, 0, v5
	v_add_u32_e32 v152, s71, v148
	s_mov_b64 s[8:9], 0x80000
	s_mov_b32 s74, 0x80000
	s_mov_b64 s[16:17], 0x90000
	s_mov_b32 s75, 0x90000
	s_mov_b64 s[18:19], 0xa0000
	s_mov_b32 s76, 0xa0000
	s_mov_b64 s[20:21], 0xb0000
	s_mov_b32 s77, 0xb0000
	s_barrier
	s_mov_b32 s98, 0

.LBB0_456:
	s_ashr_i32 s23, s22, 31
	s_lshl_b64 s[26:27], s[22:23], 18
	s_add_u32 s26, s43, s26
	s_addc_u32 s27, s44, s27
	s_and_b64 s[4:5], s[4:5], exec
	s_cselect_b32 s23, s27, s31
	s_cselect_b32 s78, s26, s30
	s_add_u32 s79, s30, 0x100
	v_mov_b32_e32 v2, 0
	s_addc_u32 s80, s31, 0
	s_mov_b32 s81, -2
	v_mov_b32_e32 v3, v2
	v_mov_b32_e32 v4, v2
	v_mov_b32_e32 v5, v2
	v_mov_b32_e32 v6, v2
	v_mov_b32_e32 v7, v2
	v_mov_b32_e32 v8, v2
	v_mov_b32_e32 v9, v2
	v_mov_b32_e32 v10, v2
	v_mov_b32_e32 v11, v2
	v_mov_b32_e32 v12, v2
	v_mov_b32_e32 v13, v2
	v_mov_b32_e32 v18, v2
	v_mov_b32_e32 v19, v2
	v_mov_b32_e32 v20, v2
	v_mov_b32_e32 v21, v2
	v_mov_b32_e32 v26, v2
	v_mov_b32_e32 v27, v2
	v_mov_b32_e32 v28, v2
	v_mov_b32_e32 v29, v2
	v_mov_b32_e32 v34, v2
	v_mov_b32_e32 v35, v2
	v_mov_b32_e32 v36, v2
	v_mov_b32_e32 v37, v2
	v_mov_b32_e32 v42, v2
	v_mov_b32_e32 v43, v2
	v_mov_b32_e32 v44, v2
	v_mov_b32_e32 v45, v2
	v_mov_b32_e32 v50, v2
	v_mov_b32_e32 v51, v2
	v_mov_b32_e32 v52, v2
	v_mov_b32_e32 v53, v2
	v_mov_b32_e32 v14, v2
	v_mov_b32_e32 v15, v2
	v_mov_b32_e32 v16, v2
	v_mov_b32_e32 v17, v2
	v_mov_b32_e32 v22, v2
	v_mov_b32_e32 v23, v2
	v_mov_b32_e32 v24, v2
	v_mov_b32_e32 v25, v2
	v_mov_b32_e32 v30, v2
	v_mov_b32_e32 v31, v2
	v_mov_b32_e32 v32, v2
	v_mov_b32_e32 v33, v2
	v_mov_b32_e32 v38, v2
	v_mov_b32_e32 v39, v2
	v_mov_b32_e32 v40, v2
	v_mov_b32_e32 v41, v2
	v_mov_b32_e32 v46, v2
	v_mov_b32_e32 v47, v2
	v_mov_b32_e32 v48, v2
	v_mov_b32_e32 v49, v2
	v_mov_b32_e32 v54, v2
	v_mov_b32_e32 v55, v2
	v_mov_b32_e32 v56, v2
	v_mov_b32_e32 v57, v2
	v_mov_b32_e32 v58, v2
	v_mov_b32_e32 v59, v2
	v_mov_b32_e32 v60, v2
	v_mov_b32_e32 v61, v2
	v_mov_b32_e32 v62, v2
	v_mov_b32_e32 v63, v2
	v_mov_b32_e32 v64, v2
	v_mov_b32_e32 v65, v2
	v_mov_b32_e32 v66, v2
	v_mov_b32_e32 v67, v2
	v_mov_b32_e32 v68, v2
	v_mov_b32_e32 v69, v2
	v_mov_b32_e32 v70, v2
	v_mov_b32_e32 v71, v2
	v_mov_b32_e32 v72, v2
	v_mov_b32_e32 v73, v2
	v_mov_b32_e32 v78, v2
	v_mov_b32_e32 v79, v2
	v_mov_b32_e32 v80, v2
	v_mov_b32_e32 v81, v2
	v_mov_b32_e32 v86, v2
	v_mov_b32_e32 v87, v2
	v_mov_b32_e32 v88, v2
	v_mov_b32_e32 v89, v2
	v_mov_b32_e32 v94, v2
	v_mov_b32_e32 v95, v2
	v_mov_b32_e32 v96, v2
	v_mov_b32_e32 v97, v2
	v_mov_b32_e32 v102, v2
	v_mov_b32_e32 v103, v2
	v_mov_b32_e32 v104, v2
	v_mov_b32_e32 v105, v2
	v_mov_b32_e32 v110, v2
	v_mov_b32_e32 v111, v2
	v_mov_b32_e32 v112, v2
	v_mov_b32_e32 v113, v2
	v_mov_b32_e32 v118, v2
	v_mov_b32_e32 v119, v2
	v_mov_b32_e32 v120, v2
	v_mov_b32_e32 v121, v2
	v_mov_b32_e32 v74, v2
	v_mov_b32_e32 v75, v2
	v_mov_b32_e32 v76, v2
	v_mov_b32_e32 v77, v2
	v_mov_b32_e32 v82, v2
	v_mov_b32_e32 v83, v2
	v_mov_b32_e32 v84, v2
	v_mov_b32_e32 v85, v2
	v_mov_b32_e32 v90, v2
	v_mov_b32_e32 v91, v2
	v_mov_b32_e32 v92, v2
	v_mov_b32_e32 v93, v2
	v_mov_b32_e32 v98, v2
	v_mov_b32_e32 v99, v2
	v_mov_b32_e32 v100, v2
	v_mov_b32_e32 v101, v2
	v_mov_b32_e32 v106, v2
	v_mov_b32_e32 v107, v2
	v_mov_b32_e32 v108, v2
	v_mov_b32_e32 v109, v2
	v_mov_b32_e32 v114, v2
	v_mov_b32_e32 v115, v2
	v_mov_b32_e32 v116, v2
	v_mov_b32_e32 v117, v2
	v_mov_b32_e32 v122, v2
	v_mov_b32_e32 v123, v2
	v_mov_b32_e32 v124, v2
	v_mov_b32_e32 v125, v2
	v_mov_b32_e32 v126, v2
	v_mov_b32_e32 v127, v2
	v_mov_b32_e32 v128, v2
	v_mov_b32_e32 v129, v2
	s_cmp_eq_u32 s98, 0
	s_cbranch_scc1 .LBB0_457
	ds_read_b128 v[154:157], v150
	ds_read_b128 v[158:161], v150 offset:1024
	ds_read_b128 v[162:165], v150 offset:2048
	ds_read_b128 v[166:169], v150 offset:3072
	s_add_u32 s4, s28, 0x100
	s_addc_u32 s5, s29, 0
	s_cmp_eq_u32 s81, 4
	s_cselect_b32 s35, s25, s5
	s_cselect_b32 s34, s24, s4
	s_cselect_b32 s31, s23, s80
	s_cselect_b32 s30, s78, s79
	v_lshl_add_u64 v[146:147], s[28:29], 0, v[138:139]
	s_add_i32 m0, s46, 0xc000
	ds_read_b128 v[170:173], v151
	ds_read_b128 v[174:177], v151 offset:1024
	ds_read_b128 v[178:181], v151 offset:2048
	ds_read_b128 v[186:189], v151 offset:3072
	ds_read_b128 v[190:193], v151 offset:4096
	ds_read_b128 v[194:197], v151 offset:5120
	ds_read_b128 v[198:201], v151 offset:6144
	ds_read_b128 v[202:205], v151 offset:7168
	global_load_lds_dwordx4 v[146:147], off
	v_lshl_add_u64 v[146:147], s[28:29], 0, v[140:141]
	s_add_i32 m0, s46, 0xe000
	s_nop 0
	global_load_lds_dwordx4 v[146:147], off
	ds_read_b128 v[206:209], v152
	ds_read_b128 v[210:213], v152 offset:1024
	ds_read_b128 v[214:217], v152 offset:2048
	ds_read_b128 v[218:221], v152 offset:3072
	s_waitcnt vmcnt(24)
	s_waitcnt lgkmcnt(0)
	s_barrier
	s_setprio 1
	v_mfma_f32_16x16x32_bf16 v[126:129], v[154:157], v[170:173], v[126:129]
	v_mfma_f32_16x16x32_bf16 v[122:125], v[162:165], v[170:173], v[122:125]
	v_mfma_f32_16x16x32_bf16 v[114:117], v[154:157], v[178:181], v[114:117]
	v_mfma_f32_16x16x32_bf16 v[106:109], v[162:165], v[178:181], v[106:109]
	v_mfma_f32_16x16x32_bf16 v[98:101], v[154:157], v[190:193], v[98:101]
	v_mfma_f32_16x16x32_bf16 v[90:93], v[162:165], v[190:193], v[90:93]
	v_mfma_f32_16x16x32_bf16 v[82:85], v[154:157], v[198:201], v[82:85]
	v_mfma_f32_16x16x32_bf16 v[74:77], v[162:165], v[198:201], v[74:77]
	v_mfma_f32_16x16x32_bf16 v[126:129], v[158:161], v[174:177], v[126:129]
	v_mfma_f32_16x16x32_bf16 v[122:125], v[166:169], v[174:177], v[122:125]
	v_mfma_f32_16x16x32_bf16 v[114:117], v[158:161], v[186:189], v[114:117]
	v_mfma_f32_16x16x32_bf16 v[106:109], v[166:169], v[186:189], v[106:109]
	v_mfma_f32_16x16x32_bf16 v[98:101], v[158:161], v[194:197], v[98:101]
	v_mfma_f32_16x16x32_bf16 v[90:93], v[166:169], v[194:197], v[90:93]
	v_mfma_f32_16x16x32_bf16 v[82:85], v[158:161], v[202:205], v[82:85]
	v_mfma_f32_16x16x32_bf16 v[74:77], v[166:169], v[202:205], v[74:77]
	v_mfma_f32_16x16x32_bf16 v[118:121], v[206:209], v[170:173], v[118:121]
	v_mfma_f32_16x16x32_bf16 v[110:113], v[214:217], v[170:173], v[110:113]
	v_mfma_f32_16x16x32_bf16 v[102:105], v[206:209], v[178:181], v[102:105]
	v_mfma_f32_16x16x32_bf16 v[94:97], v[214:217], v[178:181], v[94:97]
	v_mfma_f32_16x16x32_bf16 v[86:89], v[206:209], v[190:193], v[86:89]
	v_mfma_f32_16x16x32_bf16 v[78:81], v[214:217], v[190:193], v[78:81]
	v_mfma_f32_16x16x32_bf16 v[70:73], v[206:209], v[198:201], v[70:73]
	v_mfma_f32_16x16x32_bf16 v[66:69], v[214:217], v[198:201], v[66:69]
	v_mfma_f32_16x16x32_bf16 v[118:121], v[210:213], v[174:177], v[118:121]
	v_mfma_f32_16x16x32_bf16 v[110:113], v[218:221], v[174:177], v[110:113]
	v_mfma_f32_16x16x32_bf16 v[102:105], v[210:213], v[186:189], v[102:105]
	v_mfma_f32_16x16x32_bf16 v[94:97], v[218:221], v[186:189], v[94:97]
	v_mfma_f32_16x16x32_bf16 v[86:89], v[210:213], v[194:197], v[86:89]
	v_mfma_f32_16x16x32_bf16 v[78:81], v[218:221], v[194:197], v[78:81]
	v_mfma_f32_16x16x32_bf16 v[70:73], v[210:213], v[202:205], v[70:73]
	v_mfma_f32_16x16x32_bf16 v[66:69], v[218:221], v[202:205], v[66:69]
	s_setprio 0
	s_barrier
	s_add_i32 s28, s61, s45
	v_lshl_add_u64 v[146:147], s[30:31], 0, v[132:133]
	s_mov_b32 m0, s28
	global_load_lds_dwordx4 v[146:147], off
	v_lshl_add_u64 v[182:183], s[30:31], 0, v[136:137]
	s_add_i32 m0, s28, 0x2000
	s_nop 0
	global_load_lds_dwordx4 v[182:183], off
	s_mov_b32 m0, s46
	v_lshl_add_u64 v[222:223], s[34:35], 0, v[130:131]
	ds_read_b128 v[170:173], v151 offset:16384
	ds_read_b128 v[174:177], v151 offset:17408
	ds_read_b128 v[178:181], v151 offset:18432
	ds_read_b128 v[186:189], v151 offset:19456
	ds_read_b128 v[190:193], v151 offset:20480
	ds_read_b128 v[194:197], v151 offset:21504
	ds_read_b128 v[198:201], v151 offset:22528
	ds_read_b128 v[202:205], v151 offset:23552
	global_load_lds_dwordx4 v[222:223], off
	v_lshl_add_u64 v[224:225], s[34:35], 0, v[134:135]
	s_mov_b32 m0, s47
	s_nop 0
	global_load_lds_dwordx4 v[224:225], off
	s_waitcnt vmcnt(22)
	s_waitcnt lgkmcnt(0)
	s_barrier
	s_setprio 1
	v_mfma_f32_16x16x32_bf16 v[62:65], v[154:157], v[170:173], v[62:65]
	v_mfma_f32_16x16x32_bf16 v[58:61], v[162:165], v[170:173], v[58:61]
	v_mfma_f32_16x16x32_bf16 v[54:57], v[154:157], v[178:181], v[54:57]
	v_mfma_f32_16x16x32_bf16 v[46:49], v[162:165], v[178:181], v[46:49]
	v_mfma_f32_16x16x32_bf16 v[38:41], v[154:157], v[190:193], v[38:41]
	v_mfma_f32_16x16x32_bf16 v[30:33], v[162:165], v[190:193], v[30:33]
	v_mfma_f32_16x16x32_bf16 v[22:25], v[154:157], v[198:201], v[22:25]
	v_mfma_f32_16x16x32_bf16 v[14:17], v[162:165], v[198:201], v[14:17]
	v_mfma_f32_16x16x32_bf16 v[62:65], v[158:161], v[174:177], v[62:65]
	v_mfma_f32_16x16x32_bf16 v[58:61], v[166:169], v[174:177], v[58:61]
	v_mfma_f32_16x16x32_bf16 v[54:57], v[158:161], v[186:189], v[54:57]
	v_mfma_f32_16x16x32_bf16 v[46:49], v[166:169], v[186:189], v[46:49]
	v_mfma_f32_16x16x32_bf16 v[38:41], v[158:161], v[194:197], v[38:41]
	v_mfma_f32_16x16x32_bf16 v[30:33], v[166:169], v[194:197], v[30:33]
	v_mfma_f32_16x16x32_bf16 v[22:25], v[158:161], v[202:205], v[22:25]
	v_mfma_f32_16x16x32_bf16 v[14:17], v[166:169], v[202:205], v[14:17]
	v_mfma_f32_16x16x32_bf16 v[50:53], v[206:209], v[170:173], v[50:53]
	v_mfma_f32_16x16x32_bf16 v[42:45], v[214:217], v[170:173], v[42:45]
	v_mfma_f32_16x16x32_bf16 v[34:37], v[206:209], v[178:181], v[34:37]
	v_mfma_f32_16x16x32_bf16 v[26:29], v[214:217], v[178:181], v[26:29]
	v_mfma_f32_16x16x32_bf16 v[18:21], v[206:209], v[190:193], v[18:21]
	v_mfma_f32_16x16x32_bf16 v[10:13], v[214:217], v[190:193], v[10:13]
	v_mfma_f32_16x16x32_bf16 v[6:9], v[206:209], v[198:201], v[6:9]
	v_mfma_f32_16x16x32_bf16 v[2:5], v[214:217], v[198:201], v[2:5]
	v_mfma_f32_16x16x32_bf16 v[50:53], v[210:213], v[174:177], v[50:53]
	v_mfma_f32_16x16x32_bf16 v[42:45], v[218:221], v[174:177], v[42:45]
	v_mfma_f32_16x16x32_bf16 v[34:37], v[210:213], v[186:189], v[34:37]
	v_mfma_f32_16x16x32_bf16 v[26:29], v[218:221], v[186:189], v[26:29]
	v_mfma_f32_16x16x32_bf16 v[18:21], v[210:213], v[194:197], v[18:21]
	v_mfma_f32_16x16x32_bf16 v[10:13], v[218:221], v[194:197], v[10:13]
	v_mfma_f32_16x16x32_bf16 v[6:9], v[210:213], v[202:205], v[6:9]
	v_mfma_f32_16x16x32_bf16 v[2:5], v[218:221], v[202:205], v[2:5]
	s_setprio 0
	s_barrier
	s_add_u32 s28, s30, 0x20000
	s_addc_u32 s29, s31, 0
	s_add_i32 s82, s71, s45
	v_lshl_add_u64 v[154:155], s[28:29], 0, v[132:133]
	s_mov_b32 m0, s82
	s_nop 0
	global_load_lds_dwordx4 v[154:155], off
	v_lshl_add_u64 v[154:155], s[28:29], 0, v[136:137]
	s_add_i32 m0, s82, 0x2000
	s_nop 0
	global_load_lds_dwordx4 v[154:155], off
	s_add_i32 s82, 0, 0x18000
	v_add_u32_e32 v153, s82, v148
	ds_read_b128 v[154:157], v153
	ds_read_b128 v[158:161], v153 offset:1024
	ds_read_b128 v[162:165], v153 offset:2048
	ds_read_b128 v[166:169], v153 offset:3072
	s_add_u32 s28, s34, 0xf0000
	s_addc_u32 s29, s35, 0
	s_mov_b32 m0, s50
	v_lshl_add_u64 v[206:207], s[28:29], 0, v[130:131]
	ds_read_b128 v[170:173], v151 offset:32768
	ds_read_b128 v[174:177], v151 offset:33792
	ds_read_b128 v[178:181], v151 offset:34816
	ds_read_b128 v[186:189], v151 offset:35840
	ds_read_b128 v[190:193], v151 offset:36864
	ds_read_b128 v[194:197], v151 offset:37888
	ds_read_b128 v[198:201], v151 offset:38912
	ds_read_b128 v[202:205], v151 offset:39936
	global_load_lds_dwordx4 v[206:207], off
	v_lshl_add_u64 v[206:207], s[28:29], 0, v[134:135]
	s_mov_b32 m0, s51
	s_nop 0
	global_load_lds_dwordx4 v[206:207], off
	v_add_u32_e32 v218, 0x1c000, v148
	ds_read_b128 v[206:209], v218
	ds_read_b128 v[210:213], v218 offset:1024
	ds_read_b128 v[214:217], v218 offset:2048
	ds_read_b128 v[218:221], v218 offset:3072
	s_waitcnt vmcnt(8)
	s_waitcnt lgkmcnt(0)
	s_barrier
	s_setprio 1
	v_mfma_f32_16x16x32_bf16 v[126:129], v[154:157], v[170:173], v[126:129]
	v_mfma_f32_16x16x32_bf16 v[122:125], v[162:165], v[170:173], v[122:125]
	v_mfma_f32_16x16x32_bf16 v[114:117], v[154:157], v[178:181], v[114:117]
	v_mfma_f32_16x16x32_bf16 v[106:109], v[162:165], v[178:181], v[106:109]
	v_mfma_f32_16x16x32_bf16 v[98:101], v[154:157], v[190:193], v[98:101]
	v_mfma_f32_16x16x32_bf16 v[90:93], v[162:165], v[190:193], v[90:93]
	v_mfma_f32_16x16x32_bf16 v[82:85], v[154:157], v[198:201], v[82:85]
	v_mfma_f32_16x16x32_bf16 v[74:77], v[162:165], v[198:201], v[74:77]
	v_mfma_f32_16x16x32_bf16 v[126:129], v[158:161], v[174:177], v[126:129]
	v_mfma_f32_16x16x32_bf16 v[122:125], v[166:169], v[174:177], v[122:125]
	v_mfma_f32_16x16x32_bf16 v[114:117], v[158:161], v[186:189], v[114:117]
	v_mfma_f32_16x16x32_bf16 v[106:109], v[166:169], v[186:189], v[106:109]
	v_mfma_f32_16x16x32_bf16 v[98:101], v[158:161], v[194:197], v[98:101]
	v_mfma_f32_16x16x32_bf16 v[90:93], v[166:169], v[194:197], v[90:93]
	v_mfma_f32_16x16x32_bf16 v[82:85], v[158:161], v[202:205], v[82:85]
	v_mfma_f32_16x16x32_bf16 v[74:77], v[166:169], v[202:205], v[74:77]
	v_mfma_f32_16x16x32_bf16 v[118:121], v[206:209], v[170:173], v[118:121]
	v_mfma_f32_16x16x32_bf16 v[110:113], v[214:217], v[170:173], v[110:113]
	v_mfma_f32_16x16x32_bf16 v[102:105], v[206:209], v[178:181], v[102:105]
	v_mfma_f32_16x16x32_bf16 v[94:97], v[214:217], v[178:181], v[94:97]
	v_mfma_f32_16x16x32_bf16 v[86:89], v[206:209], v[190:193], v[86:89]
	v_mfma_f32_16x16x32_bf16 v[78:81], v[214:217], v[190:193], v[78:81]
	v_mfma_f32_16x16x32_bf16 v[70:73], v[206:209], v[198:201], v[70:73]
	v_mfma_f32_16x16x32_bf16 v[66:69], v[214:217], v[198:201], v[66:69]
	v_mfma_f32_16x16x32_bf16 v[118:121], v[210:213], v[174:177], v[118:121]
	v_mfma_f32_16x16x32_bf16 v[110:113], v[218:221], v[174:177], v[110:113]
	v_mfma_f32_16x16x32_bf16 v[102:105], v[210:213], v[186:189], v[102:105]
	v_mfma_f32_16x16x32_bf16 v[94:97], v[218:221], v[186:189], v[94:97]
	v_mfma_f32_16x16x32_bf16 v[86:89], v[210:213], v[194:197], v[86:89]
	v_mfma_f32_16x16x32_bf16 v[78:81], v[218:221], v[194:197], v[78:81]
	v_mfma_f32_16x16x32_bf16 v[70:73], v[210:213], v[202:205], v[70:73]
	v_mfma_f32_16x16x32_bf16 v[66:69], v[218:221], v[202:205], v[66:69]
	s_setprio 0
	s_barrier
	s_add_i32 s34, 0, 0x1c000
	s_add_i32 s28, s82, s45
	v_lshl_add_u64 v[146:147], v[146:147], 0, s[6:7]
	s_mov_b32 m0, s28
	global_load_lds_dwordx4 v[146:147], off
	v_lshl_add_u64 v[146:147], v[182:183], 0, s[6:7]
	s_add_i32 m0, s28, 0x2000
	s_nop 0
	global_load_lds_dwordx4 v[146:147], off
	s_mov_b32 m0, s53
	v_lshl_add_u64 v[146:147], v[222:223], 0, s[6:7]
	ds_read_b128 v[170:173], v151 offset:49152
	ds_read_b128 v[174:177], v151 offset:50176
	ds_read_b128 v[178:181], v151 offset:51200
	ds_read_b128 v[186:189], v151 offset:52224
	ds_read_b128 v[190:193], v151 offset:53248
	ds_read_b128 v[194:197], v151 offset:54272
	ds_read_b128 v[198:201], v151 offset:55296
	ds_read_b128 v[202:205], v151 offset:56320
	global_load_lds_dwordx4 v[146:147], off
	v_lshl_add_u64 v[146:147], v[224:225], 0, s[6:7]
	s_mov_b32 m0, s58
	s_nop 0
	global_load_lds_dwordx4 v[146:147], off
	s_add_u32 s28, s30, 0x20080
	s_addc_u32 s29, s31, 0
	s_add_i32 s30, s34, s45
	v_lshl_add_u64 v[146:147], s[28:29], 0, v[132:133]
	s_mov_b32 m0, s30
	s_nop 0
	global_load_lds_dwordx4 v[146:147], off
	v_lshl_add_u64 v[146:147], s[28:29], 0, v[136:137]
	s_add_i32 m0, s30, 0x2000
	s_nop 0
	global_load_lds_dwordx4 v[146:147], off
	s_waitcnt vmcnt(8)
	s_waitcnt lgkmcnt(0)
	s_barrier
	s_setprio 1
	v_mfma_f32_16x16x32_bf16 v[62:65], v[154:157], v[170:173], v[62:65]
	v_mfma_f32_16x16x32_bf16 v[58:61], v[162:165], v[170:173], v[58:61]
	v_mfma_f32_16x16x32_bf16 v[54:57], v[154:157], v[178:181], v[54:57]
	v_mfma_f32_16x16x32_bf16 v[46:49], v[162:165], v[178:181], v[46:49]
	v_mfma_f32_16x16x32_bf16 v[38:41], v[154:157], v[190:193], v[38:41]
	v_mfma_f32_16x16x32_bf16 v[30:33], v[162:165], v[190:193], v[30:33]
	v_mfma_f32_16x16x32_bf16 v[22:25], v[154:157], v[198:201], v[22:25]
	v_mfma_f32_16x16x32_bf16 v[14:17], v[162:165], v[198:201], v[14:17]
	v_mfma_f32_16x16x32_bf16 v[62:65], v[158:161], v[174:177], v[62:65]
	v_mfma_f32_16x16x32_bf16 v[58:61], v[166:169], v[174:177], v[58:61]
	v_mfma_f32_16x16x32_bf16 v[54:57], v[158:161], v[186:189], v[54:57]
	v_mfma_f32_16x16x32_bf16 v[46:49], v[166:169], v[186:189], v[46:49]
	v_mfma_f32_16x16x32_bf16 v[38:41], v[158:161], v[194:197], v[38:41]
	v_mfma_f32_16x16x32_bf16 v[30:33], v[166:169], v[194:197], v[30:33]
	v_mfma_f32_16x16x32_bf16 v[22:25], v[158:161], v[202:205], v[22:25]
	v_mfma_f32_16x16x32_bf16 v[14:17], v[166:169], v[202:205], v[14:17]
	v_mfma_f32_16x16x32_bf16 v[50:53], v[206:209], v[170:173], v[50:53]
	v_mfma_f32_16x16x32_bf16 v[42:45], v[214:217], v[170:173], v[42:45]
	v_mfma_f32_16x16x32_bf16 v[34:37], v[206:209], v[178:181], v[34:37]
	v_mfma_f32_16x16x32_bf16 v[26:29], v[214:217], v[178:181], v[26:29]
	v_mfma_f32_16x16x32_bf16 v[18:21], v[206:209], v[190:193], v[18:21]
	v_mfma_f32_16x16x32_bf16 v[10:13], v[214:217], v[190:193], v[10:13]
	v_mfma_f32_16x16x32_bf16 v[6:9], v[206:209], v[198:201], v[6:9]
	v_mfma_f32_16x16x32_bf16 v[2:5], v[214:217], v[198:201], v[2:5]
	v_mfma_f32_16x16x32_bf16 v[50:53], v[210:213], v[174:177], v[50:53]
	v_mfma_f32_16x16x32_bf16 v[42:45], v[218:221], v[174:177], v[42:45]
	v_mfma_f32_16x16x32_bf16 v[34:37], v[210:213], v[186:189], v[34:37]
	v_mfma_f32_16x16x32_bf16 v[26:29], v[218:221], v[186:189], v[26:29]
	v_mfma_f32_16x16x32_bf16 v[18:21], v[210:213], v[194:197], v[18:21]
	v_mfma_f32_16x16x32_bf16 v[10:13], v[218:221], v[194:197], v[10:13]
	v_mfma_f32_16x16x32_bf16 v[6:9], v[210:213], v[202:205], v[6:9]
	v_mfma_f32_16x16x32_bf16 v[2:5], v[218:221], v[202:205], v[2:5]
	s_setprio 0
	s_add_i32 s81, s81, 2
	s_add_u32 s79, s79, 0x100
	s_addc_u32 s80, s80, 0
	s_cmp_gt_u32 s81, 5
	s_mov_b64 s[28:29], s[4:5]
	s_barrier
	s_cbranch_scc1 .Lgemm_epi_1

.Lgemm_epi_1:
	v_lshl_add_u32 v154, s69, 8, v1
	v_lshl_or_b32 v146, s70, 8, v149
	v_ashrrev_i32_e32 v155, 31, v154
	v_ashrrev_i32_e32 v147, 31, v146
	v_lshlrev_b64 v[156:157], 12, v[154:155]
	v_lshl_add_u64 v[156:157], s[88:89], 0, v[156:157]
	v_lshlrev_b64 v[158:159], 1, v[146:147]
	v_lshl_add_u64 v[146:147], v[156:157], 0, v[158:159]
	v_cvt_pk_bf16_f32 v126, v126, v127
	v_cvt_pk_bf16_f32 v127, v128, v129
	v_cvt_pk_bf16_f32 v128, v122, v123
	v_cvt_pk_bf16_f32 v129, v124, v125
	global_store_dwordx4 v[146:147], v[126:129], off
	v_cvt_pk_bf16_f32 v118, v118, v119
	v_cvt_pk_bf16_f32 v119, v120, v121
	v_cvt_pk_bf16_f32 v120, v110, v111
	v_or_b32_e32 v110, 16, v154
	v_ashrrev_i32_e32 v111, 31, v110
	v_lshlrev_b64 v[110:111], 12, v[110:111]
	v_lshl_add_u64 v[110:111], s[88:89], 0, v[110:111]
	v_cvt_pk_bf16_f32 v121, v112, v113
	global_store_dwordx4 v[146:147], v[118:121], off offset:256
	s_mov_b32 s70, s22
	s_mov_b32 s69, s68
	v_lshl_add_u64 v[118:119], v[110:111], 0, v[158:159]
	v_cvt_pk_bf16_f32 v110, v114, v115
	v_cvt_pk_bf16_f32 v111, v116, v117
	v_cvt_pk_bf16_f32 v112, v106, v107
	v_cvt_pk_bf16_f32 v113, v108, v109
	global_store_dwordx4 v[118:119], v[110:113], off
	v_cvt_pk_bf16_f32 v102, v102, v103
	v_cvt_pk_bf16_f32 v103, v104, v105
	v_cvt_pk_bf16_f32 v104, v94, v95
	v_or_b32_e32 v94, 32, v154
	v_ashrrev_i32_e32 v95, 31, v94
	v_lshlrev_b64 v[94:95], 12, v[94:95]
	v_lshl_add_u64 v[94:95], s[88:89], 0, v[94:95]
	v_cvt_pk_bf16_f32 v105, v96, v97
	global_store_dwordx4 v[118:119], v[102:105], off offset:256
	s_mov_b64 s[30:31], s[26:27]
	s_mov_b64 s[28:29], s[24:25]
	v_lshl_add_u64 v[102:103], v[94:95], 0, v[158:159]
	v_cvt_pk_bf16_f32 v94, v98, v99
	v_cvt_pk_bf16_f32 v95, v100, v101
	v_cvt_pk_bf16_f32 v96, v90, v91
	v_cvt_pk_bf16_f32 v97, v92, v93
	global_store_dwordx4 v[102:103], v[94:97], off
	v_cvt_pk_bf16_f32 v86, v86, v87
	v_cvt_pk_bf16_f32 v87, v88, v89
	v_cvt_pk_bf16_f32 v88, v78, v79
	v_or_b32_e32 v78, 48, v154
	v_ashrrev_i32_e32 v79, 31, v78
	v_lshlrev_b64 v[78:79], 12, v[78:79]
	v_lshl_add_u64 v[78:79], s[88:89], 0, v[78:79]
	v_cvt_pk_bf16_f32 v89, v80, v81
	global_store_dwordx4 v[102:103], v[86:89], off offset:256
	s_nop 1
	v_lshl_add_u64 v[86:87], v[78:79], 0, v[158:159]
	v_cvt_pk_bf16_f32 v78, v82, v83
	v_cvt_pk_bf16_f32 v79, v84, v85
	v_cvt_pk_bf16_f32 v80, v74, v75
	v_cvt_pk_bf16_f32 v81, v76, v77
	global_store_dwordx4 v[86:87], v[78:81], off
	v_cvt_pk_bf16_f32 v70, v70, v71
	v_cvt_pk_bf16_f32 v71, v72, v73
	v_cvt_pk_bf16_f32 v72, v66, v67
	v_cvt_pk_bf16_f32 v73, v68, v69
	global_store_dwordx4 v[86:87], v[70:73], off offset:256
	v_cvt_pk_bf16_f32 v62, v62, v63
	v_cvt_pk_bf16_f32 v63, v64, v65
	v_cvt_pk_bf16_f32 v64, v58, v59
	v_add_co_u32_e32 v58, vcc, s74, v146
	v_lshl_add_u64 v[66:67], v[146:147], 0, s[8:9]
	s_nop 0
	v_addc_co_u32_e32 v59, vcc, 0, v147, vcc
	v_cvt_pk_bf16_f32 v65, v60, v61
	global_store_dwordx4 v[58:59], v[62:65], off
	v_cvt_pk_bf16_f32 v50, v50, v51
	v_cvt_pk_bf16_f32 v51, v52, v53
	v_cvt_pk_bf16_f32 v52, v42, v43
	v_cvt_pk_bf16_f32 v53, v44, v45
	global_store_dwordx4 v[66:67], v[50:53], off offset:256
	v_cvt_pk_bf16_f32 v42, v54, v55
	v_cvt_pk_bf16_f32 v43, v56, v57
	v_cvt_pk_bf16_f32 v44, v46, v47
	v_add_co_u32_e32 v46, vcc, s75, v146
	s_nop 0
	v_lshl_add_u64 v[50:51], v[146:147], 0, s[16:17]
	v_addc_co_u32_e32 v47, vcc, 0, v147, vcc
	v_cvt_pk_bf16_f32 v45, v48, v49
	global_store_dwordx4 v[46:47], v[42:45], off
	v_cvt_pk_bf16_f32 v34, v34, v35
	v_cvt_pk_bf16_f32 v35, v36, v37
	v_cvt_pk_bf16_f32 v36, v26, v27
	v_cvt_pk_bf16_f32 v37, v28, v29
	global_store_dwordx4 v[50:51], v[34:37], off offset:256
	v_cvt_pk_bf16_f32 v26, v38, v39
	v_cvt_pk_bf16_f32 v27, v40, v41
	v_cvt_pk_bf16_f32 v28, v30, v31
	v_add_co_u32_e32 v30, vcc, s76, v146
	s_nop 0
	v_lshl_add_u64 v[34:35], v[146:147], 0, s[18:19]
	v_addc_co_u32_e32 v31, vcc, 0, v147, vcc
	v_cvt_pk_bf16_f32 v29, v32, v33
	global_store_dwordx4 v[30:31], v[26:29], off
	v_cvt_pk_bf16_f32 v18, v18, v19
	v_cvt_pk_bf16_f32 v19, v20, v21
	v_cvt_pk_bf16_f32 v20, v10, v11
	v_cvt_pk_bf16_f32 v21, v12, v13
	global_store_dwordx4 v[34:35], v[18:21], off offset:256
	v_cvt_pk_bf16_f32 v10, v22, v23
	v_cvt_pk_bf16_f32 v11, v24, v25
	v_cvt_pk_bf16_f32 v12, v14, v15
	v_add_co_u32_e32 v14, vcc, s77, v146
	s_nop 0
	v_lshl_add_u64 v[18:19], v[146:147], 0, s[20:21]
	v_addc_co_u32_e32 v15, vcc, 0, v147, vcc
	s_and_b64 vcc, exec, s[2:3]
	v_cvt_pk_bf16_f32 v13, v16, v17
	global_store_dwordx4 v[14:15], v[10:13], off
	v_cvt_pk_bf16_f32 v6, v6, v7
	v_cvt_pk_bf16_f32 v7, v8, v9
	v_cvt_pk_bf16_f32 v8, v2, v3
	v_cvt_pk_bf16_f32 v9, v4, v5
	global_store_dwordx4 v[18:19], v[6:9], off offset:256
	s_mov_b32 s98, 1
	s_cbranch_vccz .LBB0_448
	s_waitcnt vmcnt(0)
	s_cmpk_gt_u32 s36, 0xff
	s_cbranch_scc1 .LBB0_461
	s_barrier

.LBB0_795:
	v_lshrrev_b32_e32 v16, 1, v6
	v_and_b32_e32 v16, 24, v16
	v_readlane_b32 s20, v252, 16
	v_and_b32_e32 v7, 15, v6
	v_lshlrev_b32_e32 v17, 1, v16
	v_lshlrev_b32_e32 v6, 2, v6
	s_lshl_b32 s2, s2, 5
	v_readlane_b32 s21, v252, 17
	v_lshl_or_b32 v160, s3, 6, v7
	v_lshl_or_b32 v7, v7, 6, v17
	s_lshl_b32 s3, s3, 13
	v_and_b32_e32 v6, 32, v6
	s_and_b32 s2, s2, 0x60
	v_lshl_add_u64 v[8:9], s[20:21], 0, v[186:187]
	v_mov_b32_e32 v145, v187
	v_bitop3_b32 v17, v7, s3, v6 bitop3:0xde
	s_lshl_b32 s3, s2, 7
	v_lshl_add_u64 v[10:11], s[20:21], 0, v[144:145]
	v_mov_b32_e32 v149, v187
	v_bitop3_b32 v161, v7, s3, v6 bitop3:0xde
	s_add_i32 m0, s16, 0x18000
	v_lshl_add_u64 v[6:7], v[8:9], 0, s[0:1]
	v_lshl_add_u64 v[12:13], s[12:13], 0, v[148:149]
	v_mov_b32_e32 v147, v187
	s_waitcnt vmcnt(2)
	s_barrier
	global_load_lds_dwordx4 v[6:7], off
	v_lshl_add_u64 v[6:7], v[10:11], 0, s[0:1]
	s_add_i32 m0, s16, 0x1a000
	s_add_i32 s38, s16, 0x8000
	v_lshl_add_u64 v[14:15], s[12:13], 0, v[146:147]
	global_load_lds_dwordx4 v[6:7], off
	v_lshl_add_u64 v[6:7], v[12:13], 0, s[0:1]
	s_mov_b32 m0, s38
	s_add_i32 s39, s16, 0xa000
	v_readlane_b32 s14, v252, 18
	global_load_lds_dwordx4 v[6:7], off
	v_lshl_add_u64 v[6:7], v[14:15], 0, s[0:1]
	s_mov_b32 m0, s39
	v_readlane_b32 s15, v252, 19
	global_load_lds_dwordx4 v[6:7], off
	s_add_i32 m0, s16, 0x1c000
	v_lshl_add_u64 v[6:7], s[14:15], 0, v[186:187]
	global_load_lds_dwordx4 v[6:7], off
	v_lshl_add_u64 v[6:7], s[14:15], 0, v[144:145]
	s_add_i32 m0, s16, 0x1e000
	v_or_b32_e32 v162, s2, v16
	global_load_lds_dwordx4 v[6:7], off
	v_lshlrev_b32_e32 v6, 15, v4
	v_and_b32_e32 v6, 0xffff0000, v6
	v_lshl_add_u32 v3, v3, 12, v6
	v_and_b32_e32 v4, 1, v4
	v_lshl_or_b32 v3, v4, 6, v3
	v_lshl_add_u32 v150, v5, 1, v3
	v_lshlrev_b32_e32 v3, 15, v0
	v_and_b32_e32 v3, 0xffff0000, v3
	s_waitcnt vmcnt(6)
	v_lshl_add_u32 v1, v1, 12, v3
	v_and_b32_e32 v0, 1, v0
	v_lshl_or_b32 v0, v0, 6, v1
	v_readlane_b32 s2, v252, 10
	s_lshl_b32 s35, s47, 13
	v_mov_b32_e32 v151, v187
	v_lshl_add_u32 v152, v2, 1, v0
	v_mov_b32_e32 v153, v187
	s_mov_b32 s40, 0
	v_add_u32_e32 v163, 0, v17
	v_readlane_b32 s41, v252, 9
	s_mov_b32 s44, s2
	s_barrier
	v_readlane_b32 s3, v252, 11
	s_mov_b32 s98, 0

.LBB0_802:
	s_ashr_i32 s15, s14, 31
	v_cmp_lt_i64_e32 vcc, s[18:19], v[190:191]
	s_lshl_b64 s[18:19], s[14:15], 20
	s_add_u32 s18, s23, s18
	s_addc_u32 s19, s26, s19
	s_and_b64 s[24:25], vcc, exec
	s_cselect_b32 s15, s19, s13
	s_cselect_b32 s45, s18, s12
	s_ashr_i32 s3, s2, 31
	s_lshl_b64 s[24:25], s[2:3], 20
	s_add_u32 s28, s73, s24
	s_addc_u32 s29, s36, s25
	s_and_b64 s[24:25], vcc, exec
	s_cselect_b32 s3, s29, s21
	s_cselect_b32 s52, s28, s20
	s_add_u32 s12, s12, 0x80080
	s_addc_u32 s13, s13, 0
	s_add_u32 s53, s20, 0x100
	v_mov_b32_e32 v0, 0
	s_addc_u32 s56, s21, 0
	s_mov_b32 s57, -2
	v_mov_b32_e32 v1, v0
	v_mov_b32_e32 v2, v0
	v_mov_b32_e32 v3, v0
	v_mov_b32_e32 v4, v0
	v_mov_b32_e32 v5, v0
	v_mov_b32_e32 v6, v0
	v_mov_b32_e32 v7, v0
	v_mov_b32_e32 v16, v0
	v_mov_b32_e32 v17, v0
	v_mov_b32_e32 v18, v0
	v_mov_b32_e32 v19, v0
	v_mov_b32_e32 v20, v0
	v_mov_b32_e32 v21, v0
	v_mov_b32_e32 v22, v0
	v_mov_b32_e32 v23, v0
	v_mov_b32_e32 v32, v0
	v_mov_b32_e32 v33, v0
	v_mov_b32_e32 v34, v0
	v_mov_b32_e32 v35, v0
	v_mov_b32_e32 v36, v0
	v_mov_b32_e32 v37, v0
	v_mov_b32_e32 v38, v0
	v_mov_b32_e32 v39, v0
	v_mov_b32_e32 v48, v0
	v_mov_b32_e32 v49, v0
	v_mov_b32_e32 v50, v0
	v_mov_b32_e32 v51, v0
	v_mov_b32_e32 v52, v0
	v_mov_b32_e32 v53, v0
	v_mov_b32_e32 v54, v0
	v_mov_b32_e32 v55, v0
	v_mov_b32_e32 v8, v0
	v_mov_b32_e32 v9, v0
	v_mov_b32_e32 v10, v0
	v_mov_b32_e32 v11, v0
	v_mov_b32_e32 v12, v0
	v_mov_b32_e32 v13, v0
	v_mov_b32_e32 v14, v0
	v_mov_b32_e32 v15, v0
	v_mov_b32_e32 v24, v0
	v_mov_b32_e32 v25, v0
	v_mov_b32_e32 v26, v0
	v_mov_b32_e32 v27, v0
	v_mov_b32_e32 v28, v0
	v_mov_b32_e32 v29, v0
	v_mov_b32_e32 v30, v0
	v_mov_b32_e32 v31, v0
	v_mov_b32_e32 v40, v0
	v_mov_b32_e32 v41, v0
	v_mov_b32_e32 v42, v0
	v_mov_b32_e32 v43, v0
	v_mov_b32_e32 v44, v0
	v_mov_b32_e32 v45, v0
	v_mov_b32_e32 v46, v0
	v_mov_b32_e32 v47, v0
	v_mov_b32_e32 v56, v0
	v_mov_b32_e32 v57, v0
	v_mov_b32_e32 v58, v0
	v_mov_b32_e32 v59, v0
	v_mov_b32_e32 v60, v0
	v_mov_b32_e32 v61, v0
	v_mov_b32_e32 v62, v0
	v_mov_b32_e32 v63, v0
	v_mov_b32_e32 v64, v0
	v_mov_b32_e32 v65, v0
	v_mov_b32_e32 v66, v0
	v_mov_b32_e32 v67, v0
	v_mov_b32_e32 v68, v0
	v_mov_b32_e32 v69, v0
	v_mov_b32_e32 v70, v0
	v_mov_b32_e32 v71, v0
	v_mov_b32_e32 v80, v0
	v_mov_b32_e32 v81, v0
	v_mov_b32_e32 v82, v0
	v_mov_b32_e32 v83, v0
	v_mov_b32_e32 v84, v0
	v_mov_b32_e32 v85, v0
	v_mov_b32_e32 v86, v0
	v_mov_b32_e32 v87, v0
	v_mov_b32_e32 v96, v0
	v_mov_b32_e32 v97, v0
	v_mov_b32_e32 v98, v0
	v_mov_b32_e32 v99, v0
	v_mov_b32_e32 v100, v0
	v_mov_b32_e32 v101, v0
	v_mov_b32_e32 v102, v0
	v_mov_b32_e32 v103, v0
	v_mov_b32_e32 v112, v0
	v_mov_b32_e32 v113, v0
	v_mov_b32_e32 v114, v0
	v_mov_b32_e32 v115, v0
	v_mov_b32_e32 v116, v0
	v_mov_b32_e32 v117, v0
	v_mov_b32_e32 v118, v0
	v_mov_b32_e32 v119, v0
	v_mov_b32_e32 v72, v0
	v_mov_b32_e32 v73, v0
	v_mov_b32_e32 v74, v0
	v_mov_b32_e32 v75, v0
	v_mov_b32_e32 v76, v0
	v_mov_b32_e32 v77, v0
	v_mov_b32_e32 v78, v0
	v_mov_b32_e32 v79, v0
	v_mov_b32_e32 v88, v0
	v_mov_b32_e32 v89, v0
	v_mov_b32_e32 v90, v0
	v_mov_b32_e32 v91, v0
	v_mov_b32_e32 v92, v0
	v_mov_b32_e32 v93, v0
	v_mov_b32_e32 v94, v0
	v_mov_b32_e32 v95, v0
	v_mov_b32_e32 v104, v0
	v_mov_b32_e32 v105, v0
	v_mov_b32_e32 v106, v0
	v_mov_b32_e32 v107, v0
	v_mov_b32_e32 v108, v0
	v_mov_b32_e32 v109, v0
	v_mov_b32_e32 v110, v0
	v_mov_b32_e32 v111, v0
	v_mov_b32_e32 v120, v0
	v_mov_b32_e32 v121, v0
	v_mov_b32_e32 v122, v0
	v_mov_b32_e32 v123, v0
	v_mov_b32_e32 v124, v0
	v_mov_b32_e32 v125, v0
	v_mov_b32_e32 v126, v0
	v_mov_b32_e32 v127, v0
	s_cmp_eq_u32 s98, 0
	s_cbranch_scc1 .LBB0_803
	s_add_u32 s4, s12, 0xfff80080
	s_addc_u32 s20, s13, -1
	s_add_i32 s58, 0, 0x10000
	v_add_u32_e32 v140, s58, v161
	ds_read_b128 v[128:131], v140
	ds_read_b128 v[132:135], v140 offset:1024
	ds_read_b128 v[136:139], v140 offset:2048
	ds_read_b128 v[140:143], v140 offset:3072
	s_cmp_eq_u32 s57, 28
	s_cselect_b32 s25, s15, s20
	s_cselect_b32 s24, s45, s4
	s_cselect_b32 s21, s3, s56
	s_cselect_b32 s20, s52, s53
	v_lshl_add_u64 v[158:159], s[12:13], 0, v[150:151]
	s_add_i32 m0, s16, 0xc000
	ds_read_b128 v[154:157], v163
	ds_read_b128 v[164:167], v163 offset:1024
	ds_read_b128 v[168:171], v163 offset:2048
	ds_read_b128 v[172:175], v163 offset:3072
	ds_read_b128 v[176:179], v163 offset:4096
	ds_read_b128 v[180:183], v163 offset:5120
	ds_read_b128 v[196:199], v163 offset:6144
	ds_read_b128 v[200:203], v163 offset:7168
	global_load_lds_dwordx4 v[158:159], off
	v_lshl_add_u64 v[158:159], s[12:13], 0, v[152:153]
	s_add_i32 m0, s16, 0xe000
	s_nop 0
	global_load_lds_dwordx4 v[158:159], off
	v_add_u32_e32 v216, 0x14000, v161
	ds_read_b128 v[204:207], v216
	ds_read_b128 v[208:211], v216 offset:1024
	ds_read_b128 v[212:215], v216 offset:2048
	ds_read_b128 v[216:219], v216 offset:3072
	s_waitcnt vmcnt(24)
	s_waitcnt lgkmcnt(0)
	s_barrier
	s_setprio 1
	v_mfma_f32_16x16x32_bf16 v[124:127], v[128:131], v[154:157], v[124:127]
	v_mfma_f32_16x16x32_bf16 v[120:123], v[136:139], v[154:157], v[120:123]
	v_mfma_f32_16x16x32_bf16 v[108:111], v[128:131], v[168:171], v[108:111]
	v_mfma_f32_16x16x32_bf16 v[104:107], v[136:139], v[168:171], v[104:107]
	v_mfma_f32_16x16x32_bf16 v[92:95], v[128:131], v[176:179], v[92:95]
	v_mfma_f32_16x16x32_bf16 v[88:91], v[136:139], v[176:179], v[88:91]
	v_mfma_f32_16x16x32_bf16 v[76:79], v[128:131], v[196:199], v[76:79]
	v_mfma_f32_16x16x32_bf16 v[72:75], v[136:139], v[196:199], v[72:75]
	v_mfma_f32_16x16x32_bf16 v[124:127], v[132:135], v[164:167], v[124:127]
	v_mfma_f32_16x16x32_bf16 v[120:123], v[140:143], v[164:167], v[120:123]
	v_mfma_f32_16x16x32_bf16 v[108:111], v[132:135], v[172:175], v[108:111]
	v_mfma_f32_16x16x32_bf16 v[104:107], v[140:143], v[172:175], v[104:107]
	v_mfma_f32_16x16x32_bf16 v[92:95], v[132:135], v[180:183], v[92:95]
	v_mfma_f32_16x16x32_bf16 v[88:91], v[140:143], v[180:183], v[88:91]
	v_mfma_f32_16x16x32_bf16 v[76:79], v[132:135], v[200:203], v[76:79]
	v_mfma_f32_16x16x32_bf16 v[72:75], v[140:143], v[200:203], v[72:75]
	v_mfma_f32_16x16x32_bf16 v[116:119], v[204:207], v[154:157], v[116:119]
	v_mfma_f32_16x16x32_bf16 v[112:115], v[212:215], v[154:157], v[112:115]
	v_mfma_f32_16x16x32_bf16 v[100:103], v[204:207], v[168:171], v[100:103]
	v_mfma_f32_16x16x32_bf16 v[96:99], v[212:215], v[168:171], v[96:99]
	v_mfma_f32_16x16x32_bf16 v[84:87], v[204:207], v[176:179], v[84:87]
	v_mfma_f32_16x16x32_bf16 v[80:83], v[212:215], v[176:179], v[80:83]
	v_mfma_f32_16x16x32_bf16 v[68:71], v[204:207], v[196:199], v[68:71]
	v_mfma_f32_16x16x32_bf16 v[64:67], v[212:215], v[196:199], v[64:67]
	v_mfma_f32_16x16x32_bf16 v[116:119], v[208:211], v[164:167], v[116:119]
	v_mfma_f32_16x16x32_bf16 v[112:115], v[216:219], v[164:167], v[112:115]
	v_mfma_f32_16x16x32_bf16 v[100:103], v[208:211], v[172:175], v[100:103]
	v_mfma_f32_16x16x32_bf16 v[96:99], v[216:219], v[172:175], v[96:99]
	v_mfma_f32_16x16x32_bf16 v[84:87], v[208:211], v[180:183], v[84:87]
	v_mfma_f32_16x16x32_bf16 v[80:83], v[216:219], v[180:183], v[80:83]
	v_mfma_f32_16x16x32_bf16 v[68:71], v[208:211], v[200:203], v[68:71]
	v_mfma_f32_16x16x32_bf16 v[64:67], v[216:219], v[200:203], v[64:67]
	s_setprio 0
	s_barrier
	s_add_i32 s4, 0, 0x14000
	s_add_i32 s58, s58, s27
	v_lshl_add_u64 v[158:159], s[20:21], 0, v[186:187]
	s_mov_b32 m0, s58
	v_lshl_add_u64 v[220:221], s[20:21], 0, v[144:145]
	global_load_lds_dwordx4 v[158:159], off
	s_add_i32 m0, s58, 0x2000
	s_nop 0
	global_load_lds_dwordx4 v[220:221], off
	s_mov_b32 m0, s16
	v_lshl_add_u64 v[222:223], s[24:25], 0, v[148:149]
	ds_read_b128 v[154:157], v163 offset:16384
	ds_read_b128 v[164:167], v163 offset:17408
	ds_read_b128 v[168:171], v163 offset:18432
	ds_read_b128 v[172:175], v163 offset:19456
	ds_read_b128 v[176:179], v163 offset:20480
	ds_read_b128 v[180:183], v163 offset:21504
	ds_read_b128 v[196:199], v163 offset:22528
	ds_read_b128 v[200:203], v163 offset:23552
	global_load_lds_dwordx4 v[222:223], off
	v_lshl_add_u64 v[224:225], s[24:25], 0, v[146:147]
	s_mov_b32 m0, s17
	s_nop 0
	global_load_lds_dwordx4 v[224:225], off
	s_waitcnt vmcnt(22)
	s_waitcnt lgkmcnt(0)
	s_barrier
	s_setprio 1
	v_mfma_f32_16x16x32_bf16 v[60:63], v[128:131], v[154:157], v[60:63]
	v_mfma_f32_16x16x32_bf16 v[56:59], v[136:139], v[154:157], v[56:59]
	v_mfma_f32_16x16x32_bf16 v[44:47], v[128:131], v[168:171], v[44:47]
	v_mfma_f32_16x16x32_bf16 v[40:43], v[136:139], v[168:171], v[40:43]
	v_mfma_f32_16x16x32_bf16 v[28:31], v[128:131], v[176:179], v[28:31]
	v_mfma_f32_16x16x32_bf16 v[24:27], v[136:139], v[176:179], v[24:27]
	v_mfma_f32_16x16x32_bf16 v[12:15], v[128:131], v[196:199], v[12:15]
	v_mfma_f32_16x16x32_bf16 v[8:11], v[136:139], v[196:199], v[8:11]
	v_mfma_f32_16x16x32_bf16 v[60:63], v[132:135], v[164:167], v[60:63]
	v_mfma_f32_16x16x32_bf16 v[56:59], v[140:143], v[164:167], v[56:59]
	v_mfma_f32_16x16x32_bf16 v[44:47], v[132:135], v[172:175], v[44:47]
	v_mfma_f32_16x16x32_bf16 v[40:43], v[140:143], v[172:175], v[40:43]
	v_mfma_f32_16x16x32_bf16 v[28:31], v[132:135], v[180:183], v[28:31]
	v_mfma_f32_16x16x32_bf16 v[24:27], v[140:143], v[180:183], v[24:27]
	v_mfma_f32_16x16x32_bf16 v[12:15], v[132:135], v[200:203], v[12:15]
	v_mfma_f32_16x16x32_bf16 v[8:11], v[140:143], v[200:203], v[8:11]
	v_mfma_f32_16x16x32_bf16 v[52:55], v[204:207], v[154:157], v[52:55]
	v_mfma_f32_16x16x32_bf16 v[48:51], v[212:215], v[154:157], v[48:51]
	v_mfma_f32_16x16x32_bf16 v[36:39], v[204:207], v[168:171], v[36:39]
	v_mfma_f32_16x16x32_bf16 v[32:35], v[212:215], v[168:171], v[32:35]
	v_mfma_f32_16x16x32_bf16 v[20:23], v[204:207], v[176:179], v[20:23]
	v_mfma_f32_16x16x32_bf16 v[16:19], v[212:215], v[176:179], v[16:19]
	v_mfma_f32_16x16x32_bf16 v[4:7], v[204:207], v[196:199], v[4:7]
	v_mfma_f32_16x16x32_bf16 v[0:3], v[212:215], v[196:199], v[0:3]
	v_mfma_f32_16x16x32_bf16 v[52:55], v[208:211], v[164:167], v[52:55]
	v_mfma_f32_16x16x32_bf16 v[48:51], v[216:219], v[164:167], v[48:51]
	v_mfma_f32_16x16x32_bf16 v[36:39], v[208:211], v[172:175], v[36:39]
	v_mfma_f32_16x16x32_bf16 v[32:35], v[216:219], v[172:175], v[32:35]
	v_mfma_f32_16x16x32_bf16 v[20:23], v[208:211], v[180:183], v[20:23]
	v_mfma_f32_16x16x32_bf16 v[16:19], v[216:219], v[180:183], v[16:19]
	v_mfma_f32_16x16x32_bf16 v[4:7], v[208:211], v[200:203], v[4:7]
	v_mfma_f32_16x16x32_bf16 v[0:3], v[216:219], v[200:203], v[0:3]
	s_setprio 0
	s_barrier
	s_add_u32 s58, s20, 0x80000
	s_addc_u32 s59, s21, 0
	s_add_i32 s4, s4, s27
	v_lshl_add_u64 v[128:129], s[58:59], 0, v[186:187]
	s_mov_b32 m0, s4
	s_nop 0
	global_load_lds_dwordx4 v[128:129], off
	v_lshl_add_u64 v[128:129], s[58:59], 0, v[144:145]
	s_add_i32 m0, s4, 0x2000
	s_nop 0
	global_load_lds_dwordx4 v[128:129], off
	s_add_i32 s4, 0, 0x18000
	v_add_u32_e32 v140, s4, v161
	ds_read_b128 v[128:131], v140
	ds_read_b128 v[132:135], v140 offset:1024
	ds_read_b128 v[136:139], v140 offset:2048
	ds_read_b128 v[140:143], v140 offset:3072
	s_add_u32 s24, s24, 0x80000
	s_addc_u32 s25, s25, 0
	s_mov_b32 m0, s30
	v_lshl_add_u64 v[204:205], s[24:25], 0, v[148:149]
	ds_read_b128 v[154:157], v163 offset:32768
	ds_read_b128 v[164:167], v163 offset:33792
	ds_read_b128 v[168:171], v163 offset:34816
	ds_read_b128 v[172:175], v163 offset:35840
	ds_read_b128 v[176:179], v163 offset:36864
	ds_read_b128 v[180:183], v163 offset:37888
	ds_read_b128 v[196:199], v163 offset:38912
	ds_read_b128 v[200:203], v163 offset:39936
	global_load_lds_dwordx4 v[204:205], off
	v_lshl_add_u64 v[204:205], s[24:25], 0, v[146:147]
	s_mov_b32 m0, s31
	s_nop 0
	global_load_lds_dwordx4 v[204:205], off
	v_add_u32_e32 v216, 0x1c000, v161
	ds_read_b128 v[204:207], v216
	ds_read_b128 v[208:211], v216 offset:1024
	ds_read_b128 v[212:215], v216 offset:2048
	ds_read_b128 v[216:219], v216 offset:3072
	s_waitcnt vmcnt(8)
	s_waitcnt lgkmcnt(0)
	s_barrier
	s_setprio 1
	v_mfma_f32_16x16x32_bf16 v[124:127], v[128:131], v[154:157], v[124:127]
	v_mfma_f32_16x16x32_bf16 v[120:123], v[136:139], v[154:157], v[120:123]
	v_mfma_f32_16x16x32_bf16 v[108:111], v[128:131], v[168:171], v[108:111]
	v_mfma_f32_16x16x32_bf16 v[104:107], v[136:139], v[168:171], v[104:107]
	v_mfma_f32_16x16x32_bf16 v[92:95], v[128:131], v[176:179], v[92:95]
	v_mfma_f32_16x16x32_bf16 v[88:91], v[136:139], v[176:179], v[88:91]
	v_mfma_f32_16x16x32_bf16 v[76:79], v[128:131], v[196:199], v[76:79]
	v_mfma_f32_16x16x32_bf16 v[72:75], v[136:139], v[196:199], v[72:75]
	v_mfma_f32_16x16x32_bf16 v[124:127], v[132:135], v[164:167], v[124:127]
	v_mfma_f32_16x16x32_bf16 v[120:123], v[140:143], v[164:167], v[120:123]
	v_mfma_f32_16x16x32_bf16 v[108:111], v[132:135], v[172:175], v[108:111]
	v_mfma_f32_16x16x32_bf16 v[104:107], v[140:143], v[172:175], v[104:107]
	v_mfma_f32_16x16x32_bf16 v[92:95], v[132:135], v[180:183], v[92:95]
	v_mfma_f32_16x16x32_bf16 v[88:91], v[140:143], v[180:183], v[88:91]
	v_mfma_f32_16x16x32_bf16 v[76:79], v[132:135], v[200:203], v[76:79]
	v_mfma_f32_16x16x32_bf16 v[72:75], v[140:143], v[200:203], v[72:75]
	v_mfma_f32_16x16x32_bf16 v[116:119], v[204:207], v[154:157], v[116:119]
	v_mfma_f32_16x16x32_bf16 v[112:115], v[212:215], v[154:157], v[112:115]
	v_mfma_f32_16x16x32_bf16 v[100:103], v[204:207], v[168:171], v[100:103]
	v_mfma_f32_16x16x32_bf16 v[96:99], v[212:215], v[168:171], v[96:99]
	v_mfma_f32_16x16x32_bf16 v[84:87], v[204:207], v[176:179], v[84:87]
	v_mfma_f32_16x16x32_bf16 v[80:83], v[212:215], v[176:179], v[80:83]
	v_mfma_f32_16x16x32_bf16 v[68:71], v[204:207], v[196:199], v[68:71]
	v_mfma_f32_16x16x32_bf16 v[64:67], v[212:215], v[196:199], v[64:67]
	v_mfma_f32_16x16x32_bf16 v[116:119], v[208:211], v[164:167], v[116:119]
	v_mfma_f32_16x16x32_bf16 v[112:115], v[216:219], v[164:167], v[112:115]
	v_mfma_f32_16x16x32_bf16 v[100:103], v[208:211], v[172:175], v[100:103]
	v_mfma_f32_16x16x32_bf16 v[96:99], v[216:219], v[172:175], v[96:99]
	v_mfma_f32_16x16x32_bf16 v[84:87], v[208:211], v[180:183], v[84:87]
	v_mfma_f32_16x16x32_bf16 v[80:83], v[216:219], v[180:183], v[80:83]
	v_mfma_f32_16x16x32_bf16 v[68:71], v[208:211], v[200:203], v[68:71]
	v_mfma_f32_16x16x32_bf16 v[64:67], v[216:219], v[200:203], v[64:67]
	s_setprio 0
	s_barrier
	s_add_i32 s24, 0, 0x1c000
	s_add_i32 s4, s4, s27
	v_lshl_add_u64 v[158:159], v[158:159], 0, s[0:1]
	s_mov_b32 m0, s4
	global_load_lds_dwordx4 v[158:159], off
	v_lshl_add_u64 v[158:159], v[220:221], 0, s[0:1]
	s_add_i32 m0, s4, 0x2000
	s_nop 0
	global_load_lds_dwordx4 v[158:159], off
	s_mov_b32 m0, s38
	v_lshl_add_u64 v[158:159], v[222:223], 0, s[0:1]
	ds_read_b128 v[154:157], v163 offset:49152
	ds_read_b128 v[164:167], v163 offset:50176
	ds_read_b128 v[168:171], v163 offset:51200
	ds_read_b128 v[172:175], v163 offset:52224
	ds_read_b128 v[176:179], v163 offset:53248
	ds_read_b128 v[180:183], v163 offset:54272
	ds_read_b128 v[196:199], v163 offset:55296
	ds_read_b128 v[200:203], v163 offset:56320
	global_load_lds_dwordx4 v[158:159], off
	v_lshl_add_u64 v[158:159], v[224:225], 0, s[0:1]
	s_mov_b32 m0, s39
	s_nop 0
	global_load_lds_dwordx4 v[158:159], off
	s_add_u32 s20, s20, 0x80080
	s_addc_u32 s21, s21, 0
	s_add_i32 s4, s24, s27
	v_lshl_add_u64 v[158:159], s[20:21], 0, v[186:187]
	s_mov_b32 m0, s4
	s_nop 0
	global_load_lds_dwordx4 v[158:159], off
	v_lshl_add_u64 v[158:159], s[20:21], 0, v[144:145]
	s_add_i32 m0, s4, 0x2000
	s_nop 0
	global_load_lds_dwordx4 v[158:159], off
	s_waitcnt vmcnt(8)
	s_waitcnt lgkmcnt(0)
	s_barrier
	s_setprio 1
	v_mfma_f32_16x16x32_bf16 v[60:63], v[128:131], v[154:157], v[60:63]
	v_mfma_f32_16x16x32_bf16 v[56:59], v[136:139], v[154:157], v[56:59]
	v_mfma_f32_16x16x32_bf16 v[44:47], v[128:131], v[168:171], v[44:47]
	v_mfma_f32_16x16x32_bf16 v[40:43], v[136:139], v[168:171], v[40:43]
	v_mfma_f32_16x16x32_bf16 v[28:31], v[128:131], v[176:179], v[28:31]
	v_mfma_f32_16x16x32_bf16 v[24:27], v[136:139], v[176:179], v[24:27]
	v_mfma_f32_16x16x32_bf16 v[12:15], v[128:131], v[196:199], v[12:15]
	v_mfma_f32_16x16x32_bf16 v[8:11], v[136:139], v[196:199], v[8:11]
	v_mfma_f32_16x16x32_bf16 v[60:63], v[132:135], v[164:167], v[60:63]
	v_mfma_f32_16x16x32_bf16 v[56:59], v[140:143], v[164:167], v[56:59]
	v_mfma_f32_16x16x32_bf16 v[44:47], v[132:135], v[172:175], v[44:47]
	v_mfma_f32_16x16x32_bf16 v[40:43], v[140:143], v[172:175], v[40:43]
	v_mfma_f32_16x16x32_bf16 v[28:31], v[132:135], v[180:183], v[28:31]
	v_mfma_f32_16x16x32_bf16 v[24:27], v[140:143], v[180:183], v[24:27]
	v_mfma_f32_16x16x32_bf16 v[12:15], v[132:135], v[200:203], v[12:15]
	v_mfma_f32_16x16x32_bf16 v[8:11], v[140:143], v[200:203], v[8:11]
	v_mfma_f32_16x16x32_bf16 v[52:55], v[204:207], v[154:157], v[52:55]
	v_mfma_f32_16x16x32_bf16 v[48:51], v[212:215], v[154:157], v[48:51]
	v_mfma_f32_16x16x32_bf16 v[36:39], v[204:207], v[168:171], v[36:39]
	v_mfma_f32_16x16x32_bf16 v[32:35], v[212:215], v[168:171], v[32:35]
	v_mfma_f32_16x16x32_bf16 v[20:23], v[204:207], v[176:179], v[20:23]
	v_mfma_f32_16x16x32_bf16 v[16:19], v[212:215], v[176:179], v[16:19]
	v_mfma_f32_16x16x32_bf16 v[4:7], v[204:207], v[196:199], v[4:7]
	v_mfma_f32_16x16x32_bf16 v[0:3], v[212:215], v[196:199], v[0:3]
	v_mfma_f32_16x16x32_bf16 v[52:55], v[208:211], v[164:167], v[52:55]
	v_mfma_f32_16x16x32_bf16 v[48:51], v[216:219], v[164:167], v[48:51]
	v_mfma_f32_16x16x32_bf16 v[36:39], v[208:211], v[172:175], v[36:39]
	v_mfma_f32_16x16x32_bf16 v[32:35], v[216:219], v[172:175], v[32:35]
	v_mfma_f32_16x16x32_bf16 v[20:23], v[208:211], v[180:183], v[20:23]
	v_mfma_f32_16x16x32_bf16 v[16:19], v[216:219], v[180:183], v[16:19]
	v_mfma_f32_16x16x32_bf16 v[4:7], v[208:211], v[200:203], v[4:7]
	v_mfma_f32_16x16x32_bf16 v[0:3], v[216:219], v[200:203], v[0:3]
	s_setprio 0
	s_add_i32 s57, s57, 2
	s_add_u32 s12, s12, 0x100
	s_addc_u32 s13, s13, 0
	s_add_u32 s53, s53, 0x100
	s_addc_u32 s56, s56, 0
	s_cmp_gt_u32 s57, 29
	s_barrier
	s_cbranch_scc1 .Lgemm_epi_2

.Lgemm_epi_2:
	s_lshl_b32 s3, s44, 8
	s_add_i32 s4, s3, s35
	v_add_u32_e32 v156, s3, v160
	s_min_i32 s3, s4, 0x4000
	v_add_u32_e32 v128, s35, v156
	s_ashr_i32 s12, s3, 11
	v_ashrrev_i32_e32 v129, 31, v128
	s_ashr_i32 s13, s12, 31
	v_lshl_add_u64 v[128:129], v[128:129], 2, s[48:49]
	s_lshl_b64 s[12:13], s[12:13], 15
	global_load_dword v167, v[128:129], off
	global_load_dword v170, v[128:129], off offset:64
	global_load_dword v171, v[128:129], off offset:128
	global_load_dword v172, v[128:129], off offset:192
	global_load_dword v173, v[128:129], off offset:512
	global_load_dword v166, v[128:129], off offset:576
	global_load_dword v165, v[128:129], off offset:640
	v_lshl_or_b32 v154, s41, 8, v162
	s_add_u32 s12, s37, s12
	s_addc_u32 s13, s6, s13
	v_ashrrev_i32_e32 v155, 31, v154
	global_load_dword v164, v[128:129], off offset:704
	v_lshl_add_u64 v[128:129], v[154:155], 2, s[12:13]
	global_load_dwordx4 v[140:143], v[128:129], off
	global_load_dwordx4 v[136:139], v[128:129], off offset:16
	global_load_dwordx4 v[132:135], v[128:129], off offset:512
	s_nop 0
	global_load_dwordx4 v[128:131], v[128:129], off offset:528
	v_ashrrev_i32_e32 v157, 31, v156
	v_lshlrev_b64 v[158:159], 1, v[154:155]
	v_lshlrev_b64 v[154:155], 14, v[156:157]
	v_lshl_add_u64 v[154:155], s[54:55], 0, v[154:155]
	v_lshl_add_u64 v[154:155], v[154:155], 0, v[158:159]
	v_or_b32_e32 v168, 16, v156
	v_ashrrev_i32_e32 v169, 31, v168
	s_mov_b32 s3, 0x200000
	s_mov_b64 s[12:13], 0x200000
	s_mov_b32 s41, s2
	s_mov_b32 s44, s14
	s_mov_b64 s[20:21], s[28:29]
	s_waitcnt vmcnt(0)
	s_nop 0
	v_fmamk_f32 v157, v167, 0x3a000000, v229
	v_mul_f32_e32 v167, 0x4b800000, v157
	v_cmp_gt_f32_e32 vcc, s5, v157
	s_nop 1
	v_cndmask_b32_e32 v157, v157, v167, vcc
	v_rsq_f32_e32 v157, v157
	v_fmamk_f32 v167, v170, 0x3a000000, v229
	v_mul_f32_e32 v170, 0x45800000, v157
	v_cndmask_b32_e32 v170, v157, v170, vcc
	v_pk_fma_f32 v[124:125], v[124:125], v[170:171], v[140:141] op_sel_hi:[1,0,1]
	v_pk_fma_f32 v[112:113], v[112:113], v[170:171], v[128:129] op_sel_hi:[1,0,1]
	v_pk_fma_f32 v[126:127], v[126:127], v[170:171], v[142:143] op_sel_hi:[1,0,1]
	v_pk_fma_f32 v[122:123], v[122:123], v[170:171], v[138:139] op_sel_hi:[1,0,1]
	v_pk_fma_f32 v[120:121], v[120:121], v[170:171], v[136:137] op_sel_hi:[1,0,1]
	v_pk_fma_f32 v[116:117], v[116:117], v[170:171], v[132:133] op_sel_hi:[1,0,1]
	v_pk_fma_f32 v[114:115], v[114:115], v[170:171], v[130:131] op_sel_hi:[1,0,1]
	v_max_f32_e32 v124, 0, v124
	v_max_f32_e32 v125, 0, v125
	v_max_f32_e32 v112, 0, v112
	v_pk_fma_f32 v[118:119], v[118:119], v[170:171], v[134:135] op_sel_hi:[1,0,1]
	v_max_f32_e32 v120, 0, v120
	v_max_f32_e32 v121, 0, v121
	v_max_f32_e32 v126, 0, v126
	v_max_f32_e32 v122, 0, v122
	v_max_f32_e32 v127, 0, v127
	v_max_f32_e32 v123, 0, v123
	v_max_f32_e32 v116, 0, v116
	v_max_f32_e32 v117, 0, v117
	v_max_f32_e32 v113, 0, v113
	v_max_f32_e32 v114, 0, v114
	v_max_f32_e32 v115, 0, v115
	v_mul_f32_e32 v124, v124, v124
	v_mul_f32_e32 v125, v125, v125
	v_mul_f32_e32 v157, v112, v112
	v_cvt_pk_bf16_f32 v112, v124, v125
	v_mul_f32_e32 v174, 0x4b800000, v167
	v_max_f32_e32 v118, 0, v118
	v_max_f32_e32 v119, 0, v119
	v_mul_f32_e32 v120, v120, v120
	v_mul_f32_e32 v121, v121, v121
	v_mul_f32_e32 v126, v126, v126
	v_mul_f32_e32 v122, v122, v122
	v_mul_f32_e32 v127, v127, v127
	v_mul_f32_e32 v123, v123, v123
	v_mul_f32_e32 v116, v116, v116
	v_mul_f32_e32 v117, v117, v117
	v_mul_f32_e32 v170, v113, v113
	v_mul_f32_e32 v175, v114, v114
	v_mul_f32_e32 v176, v115, v115
	v_cvt_pk_bf16_f32 v113, v126, v127
	v_cvt_pk_bf16_f32 v114, v120, v121
	v_cvt_pk_bf16_f32 v115, v122, v123
	global_store_dwordx4 v[154:155], v[112:115], off
	v_cmp_gt_f32_e32 vcc, s5, v167
	v_mul_f32_e32 v118, v118, v118
	v_cvt_pk_bf16_f32 v112, v116, v117
	v_mul_f32_e32 v119, v119, v119
	v_cvt_pk_bf16_f32 v113, v118, v119
	v_cvt_pk_bf16_f32 v114, v157, v170
	v_cvt_pk_bf16_f32 v115, v175, v176
	global_store_dwordx4 v[154:155], v[112:115], off offset:256
	s_nop 1
	v_cndmask_b32_e32 v112, v167, v174, vcc
	v_rsq_f32_e32 v114, v112
	v_lshlrev_b64 v[112:113], 14, v[168:169]
	v_lshl_add_u64 v[112:113], s[54:55], 0, v[112:113]
	v_lshl_add_u64 v[112:113], v[112:113], 0, v[158:159]
	v_mul_f32_e32 v115, 0x45800000, v114
	v_cndmask_b32_e32 v114, v114, v115, vcc
	v_pk_fma_f32 v[104:105], v[104:105], v[114:115], v[136:137] op_sel_hi:[1,0,1]
	v_pk_fma_f32 v[108:109], v[108:109], v[114:115], v[140:141] op_sel_hi:[1,0,1]
	v_pk_fma_f32 v[106:107], v[106:107], v[114:115], v[138:139] op_sel_hi:[1,0,1]
	v_max_f32_e32 v104, 0, v104
	v_pk_fma_f32 v[110:111], v[110:111], v[114:115], v[142:143] op_sel_hi:[1,0,1]
	v_mul_f32_e32 v115, v104, v104
	v_max_f32_e32 v104, 0, v109
	v_max_f32_e32 v105, 0, v105
	v_max_f32_e32 v106, 0, v106
	v_max_f32_e32 v108, 0, v108
	v_mul_f32_e32 v104, v104, v104
	v_mul_f32_e32 v109, v105, v105
	v_max_f32_e32 v105, 0, v110
	v_mul_f32_e32 v110, v106, v106
	v_max_f32_e32 v106, 0, v111
	v_max_f32_e32 v107, 0, v107
	v_pk_fma_f32 v[98:99], v[98:99], v[114:115], v[130:131] op_sel_hi:[1,0,1]
	v_pk_fma_f32 v[96:97], v[96:97], v[114:115], v[128:129] op_sel_hi:[1,0,1]
	v_mul_f32_e32 v108, v108, v108
	v_mul_f32_e32 v105, v105, v105
	v_mul_f32_e32 v106, v106, v106
	v_mul_f32_e32 v107, v107, v107
	v_cvt_pk_bf16_f32 v104, v108, v104
	v_pk_fma_f32 v[102:103], v[102:103], v[114:115], v[134:135] op_sel_hi:[1,0,1]
	v_pk_fma_f32 v[100:101], v[100:101], v[114:115], v[132:133] op_sel_hi:[1,0,1]
	v_max_f32_e32 v96, 0, v96
	v_max_f32_e32 v97, 0, v97
	v_max_f32_e32 v98, 0, v98
	v_cvt_pk_bf16_f32 v105, v105, v106
	v_cvt_pk_bf16_f32 v106, v115, v109
	v_cvt_pk_bf16_f32 v107, v110, v107
	global_store_dwordx4 v[112:113], v[104:107], off
	v_max_f32_e32 v100, 0, v100
	v_max_f32_e32 v99, 0, v99
	v_mul_f32_e32 v104, v96, v96
	v_max_f32_e32 v96, 0, v101
	v_mul_f32_e32 v101, v97, v97
	v_max_f32_e32 v97, 0, v102
	v_mul_f32_e32 v102, v98, v98
	v_max_f32_e32 v98, 0, v103
	v_mul_f32_e32 v96, v96, v96
	v_mul_f32_e32 v97, v97, v97
	v_mul_f32_e32 v98, v98, v98
	v_mul_f32_e32 v100, v100, v100
	v_mul_f32_e32 v99, v99, v99
	v_cvt_pk_bf16_f32 v96, v100, v96
	v_cvt_pk_bf16_f32 v97, v97, v98
	v_cvt_pk_bf16_f32 v98, v104, v101
	v_cvt_pk_bf16_f32 v99, v102, v99
	global_store_dwordx4 v[112:113], v[96:99], off offset:256
	s_nop 1
	v_fmamk_f32 v98, v171, 0x3a000000, v229
	v_mul_f32_e32 v99, 0x4b800000, v98
	v_cmp_gt_f32_e32 vcc, s5, v98
	v_or_b32_e32 v96, 32, v156
	v_ashrrev_i32_e32 v97, 31, v96
	v_cndmask_b32_e32 v98, v98, v99, vcc
	v_rsq_f32_e32 v98, v98
	v_lshlrev_b64 v[96:97], 14, v[96:97]
	v_lshl_add_u64 v[96:97], s[54:55], 0, v[96:97]
	v_lshl_add_u64 v[96:97], v[96:97], 0, v[158:159]
	v_mul_f32_e32 v99, 0x45800000, v98
	v_cndmask_b32_e32 v98, v98, v99, vcc
	v_pk_fma_f32 v[88:89], v[88:89], v[98:99], v[136:137] op_sel_hi:[1,0,1]
	v_pk_fma_f32 v[92:93], v[92:93], v[98:99], v[140:141] op_sel_hi:[1,0,1]
	v_pk_fma_f32 v[90:91], v[90:91], v[98:99], v[138:139] op_sel_hi:[1,0,1]
	v_max_f32_e32 v88, 0, v88
	v_pk_fma_f32 v[94:95], v[94:95], v[98:99], v[142:143] op_sel_hi:[1,0,1]
	v_mul_f32_e32 v99, v88, v88
	v_max_f32_e32 v88, 0, v93
	v_max_f32_e32 v89, 0, v89
	v_max_f32_e32 v90, 0, v90
	v_max_f32_e32 v92, 0, v92
	v_mul_f32_e32 v88, v88, v88
	v_mul_f32_e32 v93, v89, v89
	v_max_f32_e32 v89, 0, v94
	v_mul_f32_e32 v94, v90, v90
	v_max_f32_e32 v90, 0, v95
	v_max_f32_e32 v91, 0, v91
	v_pk_fma_f32 v[82:83], v[82:83], v[98:99], v[130:131] op_sel_hi:[1,0,1]
	v_pk_fma_f32 v[80:81], v[80:81], v[98:99], v[128:129] op_sel_hi:[1,0,1]
	v_mul_f32_e32 v92, v92, v92
	v_mul_f32_e32 v89, v89, v89
	v_mul_f32_e32 v90, v90, v90
	v_mul_f32_e32 v91, v91, v91
	v_cvt_pk_bf16_f32 v88, v92, v88
	v_pk_fma_f32 v[86:87], v[86:87], v[98:99], v[134:135] op_sel_hi:[1,0,1]
	v_pk_fma_f32 v[84:85], v[84:85], v[98:99], v[132:133] op_sel_hi:[1,0,1]
	v_max_f32_e32 v80, 0, v80
	v_max_f32_e32 v81, 0, v81
	v_max_f32_e32 v82, 0, v82
	v_cvt_pk_bf16_f32 v89, v89, v90
	v_cvt_pk_bf16_f32 v90, v99, v93
	v_cvt_pk_bf16_f32 v91, v94, v91
	global_store_dwordx4 v[96:97], v[88:91], off
	v_max_f32_e32 v84, 0, v84
	v_max_f32_e32 v83, 0, v83
	v_mul_f32_e32 v88, v80, v80
	v_max_f32_e32 v80, 0, v85
	v_mul_f32_e32 v85, v81, v81
	v_max_f32_e32 v81, 0, v86
	v_mul_f32_e32 v86, v82, v82
	v_max_f32_e32 v82, 0, v87
	v_mul_f32_e32 v80, v80, v80
	v_mul_f32_e32 v81, v81, v81
	v_mul_f32_e32 v82, v82, v82
	v_mul_f32_e32 v84, v84, v84
	v_mul_f32_e32 v83, v83, v83
	v_cvt_pk_bf16_f32 v80, v84, v80
	v_cvt_pk_bf16_f32 v81, v81, v82
	v_cvt_pk_bf16_f32 v82, v88, v85
	v_cvt_pk_bf16_f32 v83, v86, v83
	global_store_dwordx4 v[96:97], v[80:83], off offset:256
	s_nop 1
	v_fmamk_f32 v82, v172, 0x3a000000, v229
	v_mul_f32_e32 v83, 0x4b800000, v82
	v_cmp_gt_f32_e32 vcc, s5, v82
	v_or_b32_e32 v80, 48, v156
	v_ashrrev_i32_e32 v81, 31, v80
	v_cndmask_b32_e32 v82, v82, v83, vcc
	v_rsq_f32_e32 v82, v82
	v_lshlrev_b64 v[80:81], 14, v[80:81]
	v_lshl_add_u64 v[80:81], s[54:55], 0, v[80:81]
	v_lshl_add_u64 v[80:81], v[80:81], 0, v[158:159]
	v_mul_f32_e32 v83, 0x45800000, v82
	v_cndmask_b32_e32 v82, v82, v83, vcc
	v_pk_fma_f32 v[72:73], v[72:73], v[82:83], v[136:137] op_sel_hi:[1,0,1]
	v_pk_fma_f32 v[76:77], v[76:77], v[82:83], v[140:141] op_sel_hi:[1,0,1]
	v_pk_fma_f32 v[74:75], v[74:75], v[82:83], v[138:139] op_sel_hi:[1,0,1]
	v_max_f32_e32 v72, 0, v72
	v_pk_fma_f32 v[78:79], v[78:79], v[82:83], v[142:143] op_sel_hi:[1,0,1]
	v_mul_f32_e32 v83, v72, v72
	v_max_f32_e32 v72, 0, v77
	v_max_f32_e32 v73, 0, v73
	v_max_f32_e32 v74, 0, v74
	v_max_f32_e32 v76, 0, v76
	v_mul_f32_e32 v72, v72, v72
	v_mul_f32_e32 v77, v73, v73
	v_max_f32_e32 v73, 0, v78
	v_mul_f32_e32 v78, v74, v74
	v_max_f32_e32 v74, 0, v79
	v_max_f32_e32 v75, 0, v75
	v_pk_fma_f32 v[64:65], v[64:65], v[82:83], v[128:129] op_sel_hi:[1,0,1]
	v_mul_f32_e32 v76, v76, v76
	v_mul_f32_e32 v73, v73, v73
	v_mul_f32_e32 v74, v74, v74
	v_mul_f32_e32 v75, v75, v75
	v_cvt_pk_bf16_f32 v72, v76, v72
	v_pk_fma_f32 v[68:69], v[68:69], v[82:83], v[132:133] op_sel_hi:[1,0,1]
	v_pk_fma_f32 v[66:67], v[66:67], v[82:83], v[130:131] op_sel_hi:[1,0,1]
	v_max_f32_e32 v64, 0, v64
	v_cvt_pk_bf16_f32 v73, v73, v74
	v_cvt_pk_bf16_f32 v74, v83, v77
	v_cvt_pk_bf16_f32 v75, v78, v75
	global_store_dwordx4 v[80:81], v[72:75], off
	v_pk_fma_f32 v[70:71], v[70:71], v[82:83], v[134:135] op_sel_hi:[1,0,1]
	v_max_f32_e32 v68, 0, v68
	v_mul_f32_e32 v72, v64, v64
	v_max_f32_e32 v64, 0, v69
	v_max_f32_e32 v65, 0, v65
	v_max_f32_e32 v66, 0, v66
	v_mul_f32_e32 v68, v68, v68
	v_mul_f32_e32 v64, v64, v64
	v_mul_f32_e32 v69, v65, v65
	v_max_f32_e32 v65, 0, v70
	v_mul_f32_e32 v70, v66, v66
	v_max_f32_e32 v66, 0, v71
	v_mul_f32_e32 v65, v65, v65
	v_mul_f32_e32 v66, v66, v66
	v_cvt_pk_bf16_f32 v64, v68, v64
	v_fmamk_f32 v68, v173, 0x3a000000, v229
	v_cvt_pk_bf16_f32 v65, v65, v66
	v_cvt_pk_bf16_f32 v66, v72, v69
	v_mul_f32_e32 v69, 0x4b800000, v68
	v_cmp_gt_f32_e32 vcc, s5, v68
	v_max_f32_e32 v67, 0, v67
	v_mul_f32_e32 v67, v67, v67
	v_cndmask_b32_e32 v68, v68, v69, vcc
	v_rsq_f32_e32 v68, v68
	v_cvt_pk_bf16_f32 v67, v70, v67
	global_store_dwordx4 v[80:81], v[64:67], off offset:256
	s_nop 1
	v_mul_f32_e32 v66, 0x45800000, v68
	v_cndmask_b32_e32 v66, v68, v66, vcc
	v_pk_fma_f32 v[56:57], v[56:57], v[66:67], v[136:137] op_sel_hi:[1,0,1]
	v_pk_fma_f32 v[60:61], v[60:61], v[66:67], v[140:141] op_sel_hi:[1,0,1]
	v_pk_fma_f32 v[58:59], v[58:59], v[66:67], v[138:139] op_sel_hi:[1,0,1]
	v_max_f32_e32 v56, 0, v56
	v_pk_fma_f32 v[62:63], v[62:63], v[66:67], v[142:143] op_sel_hi:[1,0,1]
	v_max_f32_e32 v60, 0, v60
	v_mul_f32_e32 v67, v56, v56
	v_max_f32_e32 v56, 0, v61
	v_max_f32_e32 v57, 0, v57
	v_max_f32_e32 v58, 0, v58
	v_mul_f32_e32 v60, v60, v60
	v_mul_f32_e32 v56, v56, v56
	v_mul_f32_e32 v61, v57, v57
	v_max_f32_e32 v57, 0, v62
	v_mul_f32_e32 v62, v58, v58
	v_max_f32_e32 v58, 0, v63
	v_mul_f32_e32 v57, v57, v57
	v_max_f32_e32 v59, 0, v59
	v_mul_f32_e32 v58, v58, v58
	v_cvt_pk_bf16_f32 v56, v60, v56
	v_add_co_u32_e32 v60, vcc, s3, v154
	v_pk_fma_f32 v[48:49], v[48:49], v[66:67], v[128:129] op_sel_hi:[1,0,1]
	v_mul_f32_e32 v59, v59, v59
	v_cvt_pk_bf16_f32 v57, v57, v58
	v_cvt_pk_bf16_f32 v58, v67, v61
	v_addc_co_u32_e32 v61, vcc, 0, v155, vcc
	v_pk_fma_f32 v[52:53], v[52:53], v[66:67], v[132:133] op_sel_hi:[1,0,1]
	v_pk_fma_f32 v[50:51], v[50:51], v[66:67], v[130:131] op_sel_hi:[1,0,1]
	v_max_f32_e32 v48, 0, v48
	v_cvt_pk_bf16_f32 v59, v62, v59
	global_store_dwordx4 v[60:61], v[56:59], off
	v_pk_fma_f32 v[54:55], v[54:55], v[66:67], v[134:135] op_sel_hi:[1,0,1]
	v_max_f32_e32 v52, 0, v52
	v_mul_f32_e32 v56, v48, v48
	v_max_f32_e32 v48, 0, v53
	v_max_f32_e32 v49, 0, v49
	v_max_f32_e32 v50, 0, v50
	v_mul_f32_e32 v52, v52, v52
	v_mul_f32_e32 v48, v48, v48
	v_mul_f32_e32 v53, v49, v49
	v_max_f32_e32 v49, 0, v54
	v_mul_f32_e32 v54, v50, v50
	v_max_f32_e32 v50, 0, v55
	v_mul_f32_e32 v49, v49, v49
	v_mul_f32_e32 v50, v50, v50
	v_cvt_pk_bf16_f32 v48, v52, v48
	v_fmamk_f32 v52, v166, 0x3a000000, v229
	v_cvt_pk_bf16_f32 v49, v49, v50
	v_cvt_pk_bf16_f32 v50, v56, v53
	v_mul_f32_e32 v53, 0x4b800000, v52
	v_cmp_gt_f32_e32 vcc, s5, v52
	v_max_f32_e32 v51, 0, v51
	v_lshl_add_u64 v[64:65], v[154:155], 0, s[12:13]
	v_cndmask_b32_e32 v52, v52, v53, vcc
	v_rsq_f32_e32 v52, v52
	v_mul_f32_e32 v51, v51, v51
	v_cvt_pk_bf16_f32 v51, v54, v51
	global_store_dwordx4 v[64:65], v[48:51], off offset:256
	s_mov_b32 s3, 0x240000
	s_mov_b64 s[12:13], 0x240000
	v_mul_f32_e32 v50, 0x45800000, v52
	v_cndmask_b32_e32 v50, v52, v50, vcc
	v_pk_fma_f32 v[40:41], v[40:41], v[50:51], v[136:137] op_sel_hi:[1,0,1]
	v_pk_fma_f32 v[44:45], v[44:45], v[50:51], v[140:141] op_sel_hi:[1,0,1]
	v_pk_fma_f32 v[42:43], v[42:43], v[50:51], v[138:139] op_sel_hi:[1,0,1]
	v_max_f32_e32 v40, 0, v40
	v_pk_fma_f32 v[46:47], v[46:47], v[50:51], v[142:143] op_sel_hi:[1,0,1]
	v_max_f32_e32 v44, 0, v44
	v_mul_f32_e32 v51, v40, v40
	v_max_f32_e32 v40, 0, v45
	v_max_f32_e32 v41, 0, v41
	v_max_f32_e32 v42, 0, v42
	v_mul_f32_e32 v44, v44, v44
	v_mul_f32_e32 v40, v40, v40
	v_mul_f32_e32 v45, v41, v41
	v_max_f32_e32 v41, 0, v46
	v_mul_f32_e32 v46, v42, v42
	v_max_f32_e32 v42, 0, v47
	v_mul_f32_e32 v41, v41, v41
	v_max_f32_e32 v43, 0, v43
	v_mul_f32_e32 v42, v42, v42
	v_cvt_pk_bf16_f32 v40, v44, v40
	v_add_co_u32_e32 v44, vcc, s3, v154
	v_pk_fma_f32 v[32:33], v[32:33], v[50:51], v[128:129] op_sel_hi:[1,0,1]
	v_mul_f32_e32 v43, v43, v43
	v_cvt_pk_bf16_f32 v41, v41, v42
	v_cvt_pk_bf16_f32 v42, v51, v45
	v_addc_co_u32_e32 v45, vcc, 0, v155, vcc
	v_pk_fma_f32 v[36:37], v[36:37], v[50:51], v[132:133] op_sel_hi:[1,0,1]
	v_pk_fma_f32 v[34:35], v[34:35], v[50:51], v[130:131] op_sel_hi:[1,0,1]
	v_max_f32_e32 v32, 0, v32
	v_cvt_pk_bf16_f32 v43, v46, v43
	global_store_dwordx4 v[44:45], v[40:43], off
	v_pk_fma_f32 v[38:39], v[38:39], v[50:51], v[134:135] op_sel_hi:[1,0,1]
	v_max_f32_e32 v36, 0, v36
	v_mul_f32_e32 v40, v32, v32
	v_max_f32_e32 v32, 0, v37
	v_max_f32_e32 v33, 0, v33
	v_max_f32_e32 v34, 0, v34
	v_mul_f32_e32 v36, v36, v36
	v_mul_f32_e32 v32, v32, v32
	v_mul_f32_e32 v37, v33, v33
	v_max_f32_e32 v33, 0, v38
	v_mul_f32_e32 v38, v34, v34
	v_max_f32_e32 v34, 0, v39
	v_mul_f32_e32 v33, v33, v33
	v_mul_f32_e32 v34, v34, v34
	v_cvt_pk_bf16_f32 v32, v36, v32
	v_fmamk_f32 v36, v165, 0x3a000000, v229
	v_cvt_pk_bf16_f32 v33, v33, v34
	v_cvt_pk_bf16_f32 v34, v40, v37
	v_mul_f32_e32 v37, 0x4b800000, v36
	v_cmp_gt_f32_e32 vcc, s5, v36
	v_max_f32_e32 v35, 0, v35
	v_lshl_add_u64 v[48:49], v[154:155], 0, s[12:13]
	v_cndmask_b32_e32 v36, v36, v37, vcc
	v_rsq_f32_e32 v36, v36
	v_mul_f32_e32 v35, v35, v35
	v_cvt_pk_bf16_f32 v35, v38, v35
	global_store_dwordx4 v[48:49], v[32:35], off offset:256
	s_mov_b32 s3, 0x280000
	s_mov_b64 s[12:13], 0x280000
	v_mul_f32_e32 v34, 0x45800000, v36
	v_cndmask_b32_e32 v34, v36, v34, vcc
	v_pk_fma_f32 v[24:25], v[24:25], v[34:35], v[136:137] op_sel_hi:[1,0,1]
	v_pk_fma_f32 v[28:29], v[28:29], v[34:35], v[140:141] op_sel_hi:[1,0,1]
	v_pk_fma_f32 v[26:27], v[26:27], v[34:35], v[138:139] op_sel_hi:[1,0,1]
	v_max_f32_e32 v24, 0, v24
	v_pk_fma_f32 v[30:31], v[30:31], v[34:35], v[142:143] op_sel_hi:[1,0,1]
	v_max_f32_e32 v28, 0, v28
	v_mul_f32_e32 v35, v24, v24
	v_max_f32_e32 v24, 0, v29
	v_max_f32_e32 v25, 0, v25
	v_max_f32_e32 v26, 0, v26
	v_mul_f32_e32 v28, v28, v28
	v_mul_f32_e32 v24, v24, v24
	v_mul_f32_e32 v29, v25, v25
	v_max_f32_e32 v25, 0, v30
	v_mul_f32_e32 v30, v26, v26
	v_max_f32_e32 v26, 0, v31
	v_mul_f32_e32 v25, v25, v25
	v_max_f32_e32 v27, 0, v27
	v_mul_f32_e32 v26, v26, v26
	v_cvt_pk_bf16_f32 v24, v28, v24
	v_add_co_u32_e32 v28, vcc, s3, v154
	v_pk_fma_f32 v[16:17], v[16:17], v[34:35], v[128:129] op_sel_hi:[1,0,1]
	v_mul_f32_e32 v27, v27, v27
	v_cvt_pk_bf16_f32 v25, v25, v26
	v_cvt_pk_bf16_f32 v26, v35, v29
	v_addc_co_u32_e32 v29, vcc, 0, v155, vcc
	v_pk_fma_f32 v[20:21], v[20:21], v[34:35], v[132:133] op_sel_hi:[1,0,1]
	v_pk_fma_f32 v[18:19], v[18:19], v[34:35], v[130:131] op_sel_hi:[1,0,1]
	v_max_f32_e32 v16, 0, v16
	v_cvt_pk_bf16_f32 v27, v30, v27
	global_store_dwordx4 v[28:29], v[24:27], off
	v_pk_fma_f32 v[22:23], v[22:23], v[34:35], v[134:135] op_sel_hi:[1,0,1]
	v_max_f32_e32 v20, 0, v20
	v_mul_f32_e32 v24, v16, v16
	v_max_f32_e32 v16, 0, v21
	v_max_f32_e32 v17, 0, v17
	v_max_f32_e32 v18, 0, v18
	v_mul_f32_e32 v20, v20, v20
	v_mul_f32_e32 v16, v16, v16
	v_mul_f32_e32 v21, v17, v17
	v_max_f32_e32 v17, 0, v22
	v_mul_f32_e32 v22, v18, v18
	v_max_f32_e32 v18, 0, v23
	v_mul_f32_e32 v17, v17, v17
	v_mul_f32_e32 v18, v18, v18
	v_cvt_pk_bf16_f32 v16, v20, v16
	v_fmamk_f32 v20, v164, 0x3a000000, v229
	v_cvt_pk_bf16_f32 v17, v17, v18
	v_cvt_pk_bf16_f32 v18, v24, v21
	v_mul_f32_e32 v21, 0x4b800000, v20
	v_cmp_gt_f32_e32 vcc, s5, v20
	v_max_f32_e32 v19, 0, v19
	v_lshl_add_u64 v[32:33], v[154:155], 0, s[12:13]
	v_cndmask_b32_e32 v20, v20, v21, vcc
	v_rsq_f32_e32 v20, v20
	v_mul_f32_e32 v19, v19, v19
	v_cvt_pk_bf16_f32 v19, v22, v19
	global_store_dwordx4 v[32:33], v[16:19], off offset:256
	s_mov_b32 s3, 0x2c0000
	s_mov_b64 s[12:13], 0x2c0000
	v_mul_f32_e32 v18, 0x45800000, v20
	v_cndmask_b32_e32 v18, v20, v18, vcc
	v_pk_fma_f32 v[8:9], v[8:9], v[18:19], v[136:137] op_sel_hi:[1,0,1]
	v_pk_fma_f32 v[12:13], v[12:13], v[18:19], v[140:141] op_sel_hi:[1,0,1]
	v_pk_fma_f32 v[10:11], v[10:11], v[18:19], v[138:139] op_sel_hi:[1,0,1]
	v_max_f32_e32 v8, 0, v8
	v_pk_fma_f32 v[14:15], v[14:15], v[18:19], v[142:143] op_sel_hi:[1,0,1]
	v_max_f32_e32 v12, 0, v12
	v_mul_f32_e32 v19, v8, v8
	v_max_f32_e32 v8, 0, v13
	v_max_f32_e32 v9, 0, v9
	v_max_f32_e32 v10, 0, v10
	v_mul_f32_e32 v12, v12, v12
	v_mul_f32_e32 v8, v8, v8
	v_mul_f32_e32 v13, v9, v9
	v_max_f32_e32 v9, 0, v14
	v_mul_f32_e32 v14, v10, v10
	v_max_f32_e32 v10, 0, v15
	v_mul_f32_e32 v9, v9, v9
	v_max_f32_e32 v11, 0, v11
	v_mul_f32_e32 v10, v10, v10
	v_cvt_pk_bf16_f32 v8, v12, v8
	v_add_co_u32_e32 v12, vcc, s3, v154
	v_pk_fma_f32 v[2:3], v[2:3], v[18:19], v[130:131] op_sel_hi:[1,0,1]
	v_pk_fma_f32 v[0:1], v[0:1], v[18:19], v[128:129] op_sel_hi:[1,0,1]
	v_mul_f32_e32 v11, v11, v11
	v_cvt_pk_bf16_f32 v9, v9, v10
	v_cvt_pk_bf16_f32 v10, v19, v13
	v_addc_co_u32_e32 v13, vcc, 0, v155, vcc
	v_pk_fma_f32 v[6:7], v[6:7], v[18:19], v[134:135] op_sel_hi:[1,0,1]
	v_pk_fma_f32 v[4:5], v[4:5], v[18:19], v[132:133] op_sel_hi:[1,0,1]
	v_max_f32_e32 v0, 0, v0
	v_max_f32_e32 v1, 0, v1
	v_max_f32_e32 v2, 0, v2
	v_cvt_pk_bf16_f32 v11, v14, v11
	global_store_dwordx4 v[12:13], v[8:11], off
	v_max_f32_e32 v3, 0, v3
	v_lshl_add_u64 v[16:17], v[154:155], 0, s[12:13]
	v_mul_f32_e32 v8, v0, v0
	v_max_f32_e32 v0, 0, v5
	v_mul_f32_e32 v5, v1, v1
	v_max_f32_e32 v1, 0, v6
	v_mul_f32_e32 v6, v2, v2
	v_max_f32_e32 v2, 0, v7
	v_max_f32_e32 v4, 0, v4
	v_mul_f32_e32 v0, v0, v0
	v_mul_f32_e32 v1, v1, v1
	v_mul_f32_e32 v2, v2, v2
	v_mul_f32_e32 v3, v3, v3
	s_and_b64 vcc, exec, s[42:43]
	s_mov_b64 s[12:13], s[18:19]
	v_mul_f32_e32 v4, v4, v4
	v_cvt_pk_bf16_f32 v0, v4, v0
	v_cvt_pk_bf16_f32 v1, v1, v2
	v_cvt_pk_bf16_f32 v2, v8, v5
	v_cvt_pk_bf16_f32 v3, v6, v3
	global_store_dwordx4 v[16:17], v[0:3], off offset:256
	s_mov_b32 s98, 1
	s_cbranch_vccz .LBB0_796
	s_waitcnt vmcnt(0)
	s_cmpk_gt_u32 s22, 0xff
	v_readlane_b32 s35, v252, 37
	s_cbranch_scc1 .LBB0_807
	s_barrier
